# lever 7: phase-0 narrow dot products use v_pk_fma_f32 (two fused multiply-adds per instruction, same arithmetic)
# baseline (speedup 1.0000x reference)
.Lp0_nopf:
	v_mov_b32_e32 v128, 0
	v_mov_b32_e32 v129, 0
	v_mov_b32_e32 v130, 0
	v_mov_b32_e32 v131, 0
	v_mov_b32_e32 v132, 0
	v_mov_b32_e32 v133, 0
	v_mov_b32_e32 v134, 0
	v_mov_b32_e32 v135, 0
	v_mov_b32_e32 v136, 0
	v_mov_b32_e32 v137, 0
	v_mov_b32_e32 v138, 0
	v_mov_b32_e32 v139, 0
	v_mov_b32_e32 v140, 0
	v_mov_b32_e32 v141, 0
	v_mov_b32_e32 v142, 0
	v_mov_b32_e32 v143, 0
	v_mov_b32_e32 v254, 0
	v_mov_b32_e32 v144, 0
	v_mov_b32_e32 v145, 0
	v_mov_b32_e32 v146, 0
	v_mov_b32_e32 v147, 0
	v_mov_b32_e32 v148, 0
	v_mov_b32_e32 v149, 0
	v_mov_b32_e32 v150, 0
	v_mov_b32_e32 v151, 0
	v_mov_b32_e32 v152, 0
	v_mov_b32_e32 v153, 0
	v_mov_b32_e32 v154, 0
	v_mov_b32_e32 v155, 0
	v_mov_b32_e32 v156, 0
	v_mov_b32_e32 v157, 0
	v_mov_b32_e32 v158, 0
	v_mov_b32_e32 v159, 0
	v_mov_b32_e32 v255, 0
	ds_read_b128 v[168:171], v244 offset:0
	ds_read_b128 v[172:175], v245 offset:0
	ds_read_b128 v[176:179], v246 offset:0
	ds_read_b128 v[180:183], v247 offset:0
	ds_read_b128 v[184:187], v244 offset:4096
	ds_read_b128 v[188:191], v245 offset:4096
	ds_read_b128 v[232:235], v246 offset:4096
	ds_read_b128 v[240:243], v247 offset:4096
	v_mul_f32_e32 v252, v0, v200
	v_fmac_f32_e32 v254, v0, v0
	v_mul_f32_e32 v160, v32, v200
	v_fmac_f32_e32 v255, v32, v32
	s_waitcnt lgkmcnt(7)
	v_pk_fma_f32 v[128:129], v[252:253], v[168:169], v[128:129] op_sel_hi:[0,1,1]
	v_pk_fma_f32 v[144:145], v[160:161], v[168:169], v[144:145] op_sel_hi:[0,1,1]
	v_pk_fma_f32 v[130:131], v[252:253], v[170:171], v[130:131] op_sel_hi:[0,1,1]
	v_pk_fma_f32 v[146:147], v[160:161], v[170:171], v[146:147] op_sel_hi:[0,1,1]
	s_waitcnt lgkmcnt(6)
	v_pk_fma_f32 v[132:133], v[252:253], v[172:173], v[132:133] op_sel_hi:[0,1,1]
	v_pk_fma_f32 v[148:149], v[160:161], v[172:173], v[148:149] op_sel_hi:[0,1,1]
	v_pk_fma_f32 v[134:135], v[252:253], v[174:175], v[134:135] op_sel_hi:[0,1,1]
	v_pk_fma_f32 v[150:151], v[160:161], v[174:175], v[150:151] op_sel_hi:[0,1,1]
	s_waitcnt lgkmcnt(5)
	v_pk_fma_f32 v[136:137], v[252:253], v[176:177], v[136:137] op_sel_hi:[0,1,1]
	v_pk_fma_f32 v[152:153], v[160:161], v[176:177], v[152:153] op_sel_hi:[0,1,1]
	v_pk_fma_f32 v[138:139], v[252:253], v[178:179], v[138:139] op_sel_hi:[0,1,1]
	v_pk_fma_f32 v[154:155], v[160:161], v[178:179], v[154:155] op_sel_hi:[0,1,1]
	s_waitcnt lgkmcnt(4)
	v_pk_fma_f32 v[140:141], v[252:253], v[180:181], v[140:141] op_sel_hi:[0,1,1]
	v_pk_fma_f32 v[156:157], v[160:161], v[180:181], v[156:157] op_sel_hi:[0,1,1]
	v_pk_fma_f32 v[142:143], v[252:253], v[182:183], v[142:143] op_sel_hi:[0,1,1]
	v_pk_fma_f32 v[158:159], v[160:161], v[182:183], v[158:159] op_sel_hi:[0,1,1]
	ds_read_b128 v[168:171], v244 offset:8192
	ds_read_b128 v[172:175], v245 offset:8192
	ds_read_b128 v[176:179], v246 offset:8192
	ds_read_b128 v[180:183], v247 offset:8192
	v_mul_f32_e32 v252, v1, v201
	v_fmac_f32_e32 v254, v1, v1
	v_mul_f32_e32 v160, v33, v201
	v_fmac_f32_e32 v255, v33, v33
	s_waitcnt lgkmcnt(7)
	v_pk_fma_f32 v[128:129], v[252:253], v[184:185], v[128:129] op_sel_hi:[0,1,1]
	v_pk_fma_f32 v[144:145], v[160:161], v[184:185], v[144:145] op_sel_hi:[0,1,1]
	v_pk_fma_f32 v[130:131], v[252:253], v[186:187], v[130:131] op_sel_hi:[0,1,1]
	v_pk_fma_f32 v[146:147], v[160:161], v[186:187], v[146:147] op_sel_hi:[0,1,1]
	s_waitcnt lgkmcnt(6)
	v_pk_fma_f32 v[132:133], v[252:253], v[188:189], v[132:133] op_sel_hi:[0,1,1]
	v_pk_fma_f32 v[148:149], v[160:161], v[188:189], v[148:149] op_sel_hi:[0,1,1]
	v_pk_fma_f32 v[134:135], v[252:253], v[190:191], v[134:135] op_sel_hi:[0,1,1]
	v_pk_fma_f32 v[150:151], v[160:161], v[190:191], v[150:151] op_sel_hi:[0,1,1]
	s_waitcnt lgkmcnt(5)
	v_pk_fma_f32 v[136:137], v[252:253], v[232:233], v[136:137] op_sel_hi:[0,1,1]
	v_pk_fma_f32 v[152:153], v[160:161], v[232:233], v[152:153] op_sel_hi:[0,1,1]
	v_pk_fma_f32 v[138:139], v[252:253], v[234:235], v[138:139] op_sel_hi:[0,1,1]
	v_pk_fma_f32 v[154:155], v[160:161], v[234:235], v[154:155] op_sel_hi:[0,1,1]
	s_waitcnt lgkmcnt(4)
	v_pk_fma_f32 v[140:141], v[252:253], v[240:241], v[140:141] op_sel_hi:[0,1,1]
	v_pk_fma_f32 v[156:157], v[160:161], v[240:241], v[156:157] op_sel_hi:[0,1,1]
	v_pk_fma_f32 v[142:143], v[252:253], v[242:243], v[142:143] op_sel_hi:[0,1,1]
	v_pk_fma_f32 v[158:159], v[160:161], v[242:243], v[158:159] op_sel_hi:[0,1,1]
	ds_read_b128 v[184:187], v244 offset:12288
	ds_read_b128 v[188:191], v245 offset:12288
	ds_read_b128 v[232:235], v246 offset:12288
	ds_read_b128 v[240:243], v247 offset:12288
	v_mul_f32_e32 v252, v2, v202
	v_fmac_f32_e32 v254, v2, v2
	v_mul_f32_e32 v160, v34, v202
	v_fmac_f32_e32 v255, v34, v34
	s_waitcnt lgkmcnt(7)
	v_pk_fma_f32 v[128:129], v[252:253], v[168:169], v[128:129] op_sel_hi:[0,1,1]
	v_pk_fma_f32 v[144:145], v[160:161], v[168:169], v[144:145] op_sel_hi:[0,1,1]
	v_pk_fma_f32 v[130:131], v[252:253], v[170:171], v[130:131] op_sel_hi:[0,1,1]
	v_pk_fma_f32 v[146:147], v[160:161], v[170:171], v[146:147] op_sel_hi:[0,1,1]
	s_waitcnt lgkmcnt(6)
	v_pk_fma_f32 v[132:133], v[252:253], v[172:173], v[132:133] op_sel_hi:[0,1,1]
	v_pk_fma_f32 v[148:149], v[160:161], v[172:173], v[148:149] op_sel_hi:[0,1,1]
	v_pk_fma_f32 v[134:135], v[252:253], v[174:175], v[134:135] op_sel_hi:[0,1,1]
	v_pk_fma_f32 v[150:151], v[160:161], v[174:175], v[150:151] op_sel_hi:[0,1,1]
	s_waitcnt lgkmcnt(5)
	v_pk_fma_f32 v[136:137], v[252:253], v[176:177], v[136:137] op_sel_hi:[0,1,1]
	v_pk_fma_f32 v[152:153], v[160:161], v[176:177], v[152:153] op_sel_hi:[0,1,1]
	v_pk_fma_f32 v[138:139], v[252:253], v[178:179], v[138:139] op_sel_hi:[0,1,1]
	v_pk_fma_f32 v[154:155], v[160:161], v[178:179], v[154:155] op_sel_hi:[0,1,1]
	s_waitcnt lgkmcnt(4)
	v_pk_fma_f32 v[140:141], v[252:253], v[180:181], v[140:141] op_sel_hi:[0,1,1]
	v_pk_fma_f32 v[156:157], v[160:161], v[180:181], v[156:157] op_sel_hi:[0,1,1]
	v_pk_fma_f32 v[142:143], v[252:253], v[182:183], v[142:143] op_sel_hi:[0,1,1]
	v_pk_fma_f32 v[158:159], v[160:161], v[182:183], v[158:159] op_sel_hi:[0,1,1]
	ds_read_b128 v[168:171], v244 offset:16384
	ds_read_b128 v[172:175], v245 offset:16384
	ds_read_b128 v[176:179], v246 offset:16384
	ds_read_b128 v[180:183], v247 offset:16384
	v_mul_f32_e32 v252, v3, v203
	v_fmac_f32_e32 v254, v3, v3
	v_mul_f32_e32 v160, v35, v203
	v_fmac_f32_e32 v255, v35, v35
	s_waitcnt lgkmcnt(7)
	v_pk_fma_f32 v[128:129], v[252:253], v[184:185], v[128:129] op_sel_hi:[0,1,1]
	v_pk_fma_f32 v[144:145], v[160:161], v[184:185], v[144:145] op_sel_hi:[0,1,1]
	v_pk_fma_f32 v[130:131], v[252:253], v[186:187], v[130:131] op_sel_hi:[0,1,1]
	v_pk_fma_f32 v[146:147], v[160:161], v[186:187], v[146:147] op_sel_hi:[0,1,1]
	s_waitcnt lgkmcnt(6)
	v_pk_fma_f32 v[132:133], v[252:253], v[188:189], v[132:133] op_sel_hi:[0,1,1]
	v_pk_fma_f32 v[148:149], v[160:161], v[188:189], v[148:149] op_sel_hi:[0,1,1]
	v_pk_fma_f32 v[134:135], v[252:253], v[190:191], v[134:135] op_sel_hi:[0,1,1]
	v_pk_fma_f32 v[150:151], v[160:161], v[190:191], v[150:151] op_sel_hi:[0,1,1]
	s_waitcnt lgkmcnt(5)
	v_pk_fma_f32 v[136:137], v[252:253], v[232:233], v[136:137] op_sel_hi:[0,1,1]
	v_pk_fma_f32 v[152:153], v[160:161], v[232:233], v[152:153] op_sel_hi:[0,1,1]
	v_pk_fma_f32 v[138:139], v[252:253], v[234:235], v[138:139] op_sel_hi:[0,1,1]
	v_pk_fma_f32 v[154:155], v[160:161], v[234:235], v[154:155] op_sel_hi:[0,1,1]
	s_waitcnt lgkmcnt(4)
	v_pk_fma_f32 v[140:141], v[252:253], v[240:241], v[140:141] op_sel_hi:[0,1,1]
	v_pk_fma_f32 v[156:157], v[160:161], v[240:241], v[156:157] op_sel_hi:[0,1,1]
	v_pk_fma_f32 v[142:143], v[252:253], v[242:243], v[142:143] op_sel_hi:[0,1,1]
	v_pk_fma_f32 v[158:159], v[160:161], v[242:243], v[158:159] op_sel_hi:[0,1,1]
	ds_read_b128 v[184:187], v244 offset:20480
	ds_read_b128 v[188:191], v245 offset:20480
	ds_read_b128 v[232:235], v246 offset:20480
	ds_read_b128 v[240:243], v247 offset:20480
	v_mul_f32_e32 v252, v4, v204
	v_fmac_f32_e32 v254, v4, v4
	v_mul_f32_e32 v160, v36, v204
	v_fmac_f32_e32 v255, v36, v36
	s_waitcnt lgkmcnt(7)
	v_pk_fma_f32 v[128:129], v[252:253], v[168:169], v[128:129] op_sel_hi:[0,1,1]
	v_pk_fma_f32 v[144:145], v[160:161], v[168:169], v[144:145] op_sel_hi:[0,1,1]
	v_pk_fma_f32 v[130:131], v[252:253], v[170:171], v[130:131] op_sel_hi:[0,1,1]
	v_pk_fma_f32 v[146:147], v[160:161], v[170:171], v[146:147] op_sel_hi:[0,1,1]
	s_waitcnt lgkmcnt(6)
	v_pk_fma_f32 v[132:133], v[252:253], v[172:173], v[132:133] op_sel_hi:[0,1,1]
	v_pk_fma_f32 v[148:149], v[160:161], v[172:173], v[148:149] op_sel_hi:[0,1,1]
	v_pk_fma_f32 v[134:135], v[252:253], v[174:175], v[134:135] op_sel_hi:[0,1,1]
	v_pk_fma_f32 v[150:151], v[160:161], v[174:175], v[150:151] op_sel_hi:[0,1,1]
	s_waitcnt lgkmcnt(5)
	v_pk_fma_f32 v[136:137], v[252:253], v[176:177], v[136:137] op_sel_hi:[0,1,1]
	v_pk_fma_f32 v[152:153], v[160:161], v[176:177], v[152:153] op_sel_hi:[0,1,1]
	v_pk_fma_f32 v[138:139], v[252:253], v[178:179], v[138:139] op_sel_hi:[0,1,1]
	v_pk_fma_f32 v[154:155], v[160:161], v[178:179], v[154:155] op_sel_hi:[0,1,1]
	s_waitcnt lgkmcnt(4)
	v_pk_fma_f32 v[140:141], v[252:253], v[180:181], v[140:141] op_sel_hi:[0,1,1]
	v_pk_fma_f32 v[156:157], v[160:161], v[180:181], v[156:157] op_sel_hi:[0,1,1]
	v_pk_fma_f32 v[142:143], v[252:253], v[182:183], v[142:143] op_sel_hi:[0,1,1]
	v_pk_fma_f32 v[158:159], v[160:161], v[182:183], v[158:159] op_sel_hi:[0,1,1]
	ds_read_b128 v[168:171], v244 offset:24576
	ds_read_b128 v[172:175], v245 offset:24576
	ds_read_b128 v[176:179], v246 offset:24576
	ds_read_b128 v[180:183], v247 offset:24576
	v_mul_f32_e32 v252, v5, v205
	v_fmac_f32_e32 v254, v5, v5
	v_mul_f32_e32 v160, v37, v205
	v_fmac_f32_e32 v255, v37, v37
	s_waitcnt lgkmcnt(7)
	v_pk_fma_f32 v[128:129], v[252:253], v[184:185], v[128:129] op_sel_hi:[0,1,1]
	v_pk_fma_f32 v[144:145], v[160:161], v[184:185], v[144:145] op_sel_hi:[0,1,1]
	v_pk_fma_f32 v[130:131], v[252:253], v[186:187], v[130:131] op_sel_hi:[0,1,1]
	v_pk_fma_f32 v[146:147], v[160:161], v[186:187], v[146:147] op_sel_hi:[0,1,1]
	s_waitcnt lgkmcnt(6)
	v_pk_fma_f32 v[132:133], v[252:253], v[188:189], v[132:133] op_sel_hi:[0,1,1]
	v_pk_fma_f32 v[148:149], v[160:161], v[188:189], v[148:149] op_sel_hi:[0,1,1]
	v_pk_fma_f32 v[134:135], v[252:253], v[190:191], v[134:135] op_sel_hi:[0,1,1]
	v_pk_fma_f32 v[150:151], v[160:161], v[190:191], v[150:151] op_sel_hi:[0,1,1]
	s_waitcnt lgkmcnt(5)
	v_pk_fma_f32 v[136:137], v[252:253], v[232:233], v[136:137] op_sel_hi:[0,1,1]
	v_pk_fma_f32 v[152:153], v[160:161], v[232:233], v[152:153] op_sel_hi:[0,1,1]
	v_pk_fma_f32 v[138:139], v[252:253], v[234:235], v[138:139] op_sel_hi:[0,1,1]
	v_pk_fma_f32 v[154:155], v[160:161], v[234:235], v[154:155] op_sel_hi:[0,1,1]
	s_waitcnt lgkmcnt(4)
	v_pk_fma_f32 v[140:141], v[252:253], v[240:241], v[140:141] op_sel_hi:[0,1,1]
	v_pk_fma_f32 v[156:157], v[160:161], v[240:241], v[156:157] op_sel_hi:[0,1,1]
	v_pk_fma_f32 v[142:143], v[252:253], v[242:243], v[142:143] op_sel_hi:[0,1,1]
	v_pk_fma_f32 v[158:159], v[160:161], v[242:243], v[158:159] op_sel_hi:[0,1,1]
	ds_read_b128 v[184:187], v244 offset:28672
	ds_read_b128 v[188:191], v245 offset:28672
	ds_read_b128 v[232:235], v246 offset:28672
	ds_read_b128 v[240:243], v247 offset:28672
	v_mul_f32_e32 v252, v6, v206
	v_fmac_f32_e32 v254, v6, v6
	v_mul_f32_e32 v160, v38, v206
	v_fmac_f32_e32 v255, v38, v38
	s_waitcnt lgkmcnt(7)
	v_pk_fma_f32 v[128:129], v[252:253], v[168:169], v[128:129] op_sel_hi:[0,1,1]
	v_pk_fma_f32 v[144:145], v[160:161], v[168:169], v[144:145] op_sel_hi:[0,1,1]
	v_pk_fma_f32 v[130:131], v[252:253], v[170:171], v[130:131] op_sel_hi:[0,1,1]
	v_pk_fma_f32 v[146:147], v[160:161], v[170:171], v[146:147] op_sel_hi:[0,1,1]
	s_waitcnt lgkmcnt(6)
	v_pk_fma_f32 v[132:133], v[252:253], v[172:173], v[132:133] op_sel_hi:[0,1,1]
	v_pk_fma_f32 v[148:149], v[160:161], v[172:173], v[148:149] op_sel_hi:[0,1,1]
	v_pk_fma_f32 v[134:135], v[252:253], v[174:175], v[134:135] op_sel_hi:[0,1,1]
	v_pk_fma_f32 v[150:151], v[160:161], v[174:175], v[150:151] op_sel_hi:[0,1,1]
	s_waitcnt lgkmcnt(5)
	v_pk_fma_f32 v[136:137], v[252:253], v[176:177], v[136:137] op_sel_hi:[0,1,1]
	v_pk_fma_f32 v[152:153], v[160:161], v[176:177], v[152:153] op_sel_hi:[0,1,1]
	v_pk_fma_f32 v[138:139], v[252:253], v[178:179], v[138:139] op_sel_hi:[0,1,1]
	v_pk_fma_f32 v[154:155], v[160:161], v[178:179], v[154:155] op_sel_hi:[0,1,1]
	s_waitcnt lgkmcnt(4)
	v_pk_fma_f32 v[140:141], v[252:253], v[180:181], v[140:141] op_sel_hi:[0,1,1]
	v_pk_fma_f32 v[156:157], v[160:161], v[180:181], v[156:157] op_sel_hi:[0,1,1]
	v_pk_fma_f32 v[142:143], v[252:253], v[182:183], v[142:143] op_sel_hi:[0,1,1]
	v_pk_fma_f32 v[158:159], v[160:161], v[182:183], v[158:159] op_sel_hi:[0,1,1]
	ds_read_b128 v[168:171], v244 offset:32768
	ds_read_b128 v[172:175], v245 offset:32768
	ds_read_b128 v[176:179], v246 offset:32768
	ds_read_b128 v[180:183], v247 offset:32768
	v_mul_f32_e32 v252, v7, v207
	v_fmac_f32_e32 v254, v7, v7
	v_mul_f32_e32 v160, v39, v207
	v_fmac_f32_e32 v255, v39, v39
	s_waitcnt lgkmcnt(7)
	v_pk_fma_f32 v[128:129], v[252:253], v[184:185], v[128:129] op_sel_hi:[0,1,1]
	v_pk_fma_f32 v[144:145], v[160:161], v[184:185], v[144:145] op_sel_hi:[0,1,1]
	v_pk_fma_f32 v[130:131], v[252:253], v[186:187], v[130:131] op_sel_hi:[0,1,1]
	v_pk_fma_f32 v[146:147], v[160:161], v[186:187], v[146:147] op_sel_hi:[0,1,1]
	s_waitcnt lgkmcnt(6)
	v_pk_fma_f32 v[132:133], v[252:253], v[188:189], v[132:133] op_sel_hi:[0,1,1]
	v_pk_fma_f32 v[148:149], v[160:161], v[188:189], v[148:149] op_sel_hi:[0,1,1]
	v_pk_fma_f32 v[134:135], v[252:253], v[190:191], v[134:135] op_sel_hi:[0,1,1]
	v_pk_fma_f32 v[150:151], v[160:161], v[190:191], v[150:151] op_sel_hi:[0,1,1]
	s_waitcnt lgkmcnt(5)
	v_pk_fma_f32 v[136:137], v[252:253], v[232:233], v[136:137] op_sel_hi:[0,1,1]
	v_pk_fma_f32 v[152:153], v[160:161], v[232:233], v[152:153] op_sel_hi:[0,1,1]
	v_pk_fma_f32 v[138:139], v[252:253], v[234:235], v[138:139] op_sel_hi:[0,1,1]
	v_pk_fma_f32 v[154:155], v[160:161], v[234:235], v[154:155] op_sel_hi:[0,1,1]
	s_waitcnt lgkmcnt(4)
	v_pk_fma_f32 v[140:141], v[252:253], v[240:241], v[140:141] op_sel_hi:[0,1,1]
	v_pk_fma_f32 v[156:157], v[160:161], v[240:241], v[156:157] op_sel_hi:[0,1,1]
	v_pk_fma_f32 v[142:143], v[252:253], v[242:243], v[142:143] op_sel_hi:[0,1,1]
	v_pk_fma_f32 v[158:159], v[160:161], v[242:243], v[158:159] op_sel_hi:[0,1,1]
	ds_read_b128 v[184:187], v244 offset:36864
	ds_read_b128 v[188:191], v245 offset:36864
	ds_read_b128 v[232:235], v246 offset:36864
	ds_read_b128 v[240:243], v247 offset:36864
	v_mul_f32_e32 v252, v8, v208
	v_fmac_f32_e32 v254, v8, v8
	v_mul_f32_e32 v160, v40, v208
	v_fmac_f32_e32 v255, v40, v40
	s_waitcnt lgkmcnt(7)
	v_pk_fma_f32 v[128:129], v[252:253], v[168:169], v[128:129] op_sel_hi:[0,1,1]
	v_pk_fma_f32 v[144:145], v[160:161], v[168:169], v[144:145] op_sel_hi:[0,1,1]
	v_pk_fma_f32 v[130:131], v[252:253], v[170:171], v[130:131] op_sel_hi:[0,1,1]
	v_pk_fma_f32 v[146:147], v[160:161], v[170:171], v[146:147] op_sel_hi:[0,1,1]
	s_waitcnt lgkmcnt(6)
	v_pk_fma_f32 v[132:133], v[252:253], v[172:173], v[132:133] op_sel_hi:[0,1,1]
	v_pk_fma_f32 v[148:149], v[160:161], v[172:173], v[148:149] op_sel_hi:[0,1,1]
	v_pk_fma_f32 v[134:135], v[252:253], v[174:175], v[134:135] op_sel_hi:[0,1,1]
	v_pk_fma_f32 v[150:151], v[160:161], v[174:175], v[150:151] op_sel_hi:[0,1,1]
	s_waitcnt lgkmcnt(5)
	v_pk_fma_f32 v[136:137], v[252:253], v[176:177], v[136:137] op_sel_hi:[0,1,1]
	v_pk_fma_f32 v[152:153], v[160:161], v[176:177], v[152:153] op_sel_hi:[0,1,1]
	v_pk_fma_f32 v[138:139], v[252:253], v[178:179], v[138:139] op_sel_hi:[0,1,1]
	v_pk_fma_f32 v[154:155], v[160:161], v[178:179], v[154:155] op_sel_hi:[0,1,1]
	s_waitcnt lgkmcnt(4)
	v_pk_fma_f32 v[140:141], v[252:253], v[180:181], v[140:141] op_sel_hi:[0,1,1]
	v_pk_fma_f32 v[156:157], v[160:161], v[180:181], v[156:157] op_sel_hi:[0,1,1]
	v_pk_fma_f32 v[142:143], v[252:253], v[182:183], v[142:143] op_sel_hi:[0,1,1]
	v_pk_fma_f32 v[158:159], v[160:161], v[182:183], v[158:159] op_sel_hi:[0,1,1]
	ds_read_b128 v[168:171], v244 offset:40960
	ds_read_b128 v[172:175], v245 offset:40960
	ds_read_b128 v[176:179], v246 offset:40960
	ds_read_b128 v[180:183], v247 offset:40960
	v_mul_f32_e32 v252, v9, v209
	v_fmac_f32_e32 v254, v9, v9
	v_mul_f32_e32 v160, v41, v209
	v_fmac_f32_e32 v255, v41, v41
	s_waitcnt lgkmcnt(7)
	v_pk_fma_f32 v[128:129], v[252:253], v[184:185], v[128:129] op_sel_hi:[0,1,1]
	v_pk_fma_f32 v[144:145], v[160:161], v[184:185], v[144:145] op_sel_hi:[0,1,1]
	v_pk_fma_f32 v[130:131], v[252:253], v[186:187], v[130:131] op_sel_hi:[0,1,1]
	v_pk_fma_f32 v[146:147], v[160:161], v[186:187], v[146:147] op_sel_hi:[0,1,1]
	s_waitcnt lgkmcnt(6)
	v_pk_fma_f32 v[132:133], v[252:253], v[188:189], v[132:133] op_sel_hi:[0,1,1]
	v_pk_fma_f32 v[148:149], v[160:161], v[188:189], v[148:149] op_sel_hi:[0,1,1]
	v_pk_fma_f32 v[134:135], v[252:253], v[190:191], v[134:135] op_sel_hi:[0,1,1]
	v_pk_fma_f32 v[150:151], v[160:161], v[190:191], v[150:151] op_sel_hi:[0,1,1]
	s_waitcnt lgkmcnt(5)
	v_pk_fma_f32 v[136:137], v[252:253], v[232:233], v[136:137] op_sel_hi:[0,1,1]
	v_pk_fma_f32 v[152:153], v[160:161], v[232:233], v[152:153] op_sel_hi:[0,1,1]
	v_pk_fma_f32 v[138:139], v[252:253], v[234:235], v[138:139] op_sel_hi:[0,1,1]
	v_pk_fma_f32 v[154:155], v[160:161], v[234:235], v[154:155] op_sel_hi:[0,1,1]
	s_waitcnt lgkmcnt(4)
	v_pk_fma_f32 v[140:141], v[252:253], v[240:241], v[140:141] op_sel_hi:[0,1,1]
	v_pk_fma_f32 v[156:157], v[160:161], v[240:241], v[156:157] op_sel_hi:[0,1,1]
	v_pk_fma_f32 v[142:143], v[252:253], v[242:243], v[142:143] op_sel_hi:[0,1,1]
	v_pk_fma_f32 v[158:159], v[160:161], v[242:243], v[158:159] op_sel_hi:[0,1,1]
	ds_read_b128 v[184:187], v244 offset:45056
	ds_read_b128 v[188:191], v245 offset:45056
	ds_read_b128 v[232:235], v246 offset:45056
	ds_read_b128 v[240:243], v247 offset:45056
	v_mul_f32_e32 v252, v10, v210
	v_fmac_f32_e32 v254, v10, v10
	v_mul_f32_e32 v160, v42, v210
	v_fmac_f32_e32 v255, v42, v42
	s_waitcnt lgkmcnt(7)
	v_pk_fma_f32 v[128:129], v[252:253], v[168:169], v[128:129] op_sel_hi:[0,1,1]
	v_pk_fma_f32 v[144:145], v[160:161], v[168:169], v[144:145] op_sel_hi:[0,1,1]
	v_pk_fma_f32 v[130:131], v[252:253], v[170:171], v[130:131] op_sel_hi:[0,1,1]
	v_pk_fma_f32 v[146:147], v[160:161], v[170:171], v[146:147] op_sel_hi:[0,1,1]
	s_waitcnt lgkmcnt(6)
	v_pk_fma_f32 v[132:133], v[252:253], v[172:173], v[132:133] op_sel_hi:[0,1,1]
	v_pk_fma_f32 v[148:149], v[160:161], v[172:173], v[148:149] op_sel_hi:[0,1,1]
	v_pk_fma_f32 v[134:135], v[252:253], v[174:175], v[134:135] op_sel_hi:[0,1,1]
	v_pk_fma_f32 v[150:151], v[160:161], v[174:175], v[150:151] op_sel_hi:[0,1,1]
	s_waitcnt lgkmcnt(5)
	v_pk_fma_f32 v[136:137], v[252:253], v[176:177], v[136:137] op_sel_hi:[0,1,1]
	v_pk_fma_f32 v[152:153], v[160:161], v[176:177], v[152:153] op_sel_hi:[0,1,1]
	v_pk_fma_f32 v[138:139], v[252:253], v[178:179], v[138:139] op_sel_hi:[0,1,1]
	v_pk_fma_f32 v[154:155], v[160:161], v[178:179], v[154:155] op_sel_hi:[0,1,1]
	s_waitcnt lgkmcnt(4)
	v_pk_fma_f32 v[140:141], v[252:253], v[180:181], v[140:141] op_sel_hi:[0,1,1]
	v_pk_fma_f32 v[156:157], v[160:161], v[180:181], v[156:157] op_sel_hi:[0,1,1]
	v_pk_fma_f32 v[142:143], v[252:253], v[182:183], v[142:143] op_sel_hi:[0,1,1]
	v_pk_fma_f32 v[158:159], v[160:161], v[182:183], v[158:159] op_sel_hi:[0,1,1]
	ds_read_b128 v[168:171], v244 offset:49152
	ds_read_b128 v[172:175], v245 offset:49152
	ds_read_b128 v[176:179], v246 offset:49152
	ds_read_b128 v[180:183], v247 offset:49152
	v_mul_f32_e32 v252, v11, v211
	v_fmac_f32_e32 v254, v11, v11
	v_mul_f32_e32 v160, v43, v211
	v_fmac_f32_e32 v255, v43, v43
	s_waitcnt lgkmcnt(7)
	v_pk_fma_f32 v[128:129], v[252:253], v[184:185], v[128:129] op_sel_hi:[0,1,1]
	v_pk_fma_f32 v[144:145], v[160:161], v[184:185], v[144:145] op_sel_hi:[0,1,1]
	v_pk_fma_f32 v[130:131], v[252:253], v[186:187], v[130:131] op_sel_hi:[0,1,1]
	v_pk_fma_f32 v[146:147], v[160:161], v[186:187], v[146:147] op_sel_hi:[0,1,1]
	s_waitcnt lgkmcnt(6)
	v_pk_fma_f32 v[132:133], v[252:253], v[188:189], v[132:133] op_sel_hi:[0,1,1]
	v_pk_fma_f32 v[148:149], v[160:161], v[188:189], v[148:149] op_sel_hi:[0,1,1]
	v_pk_fma_f32 v[134:135], v[252:253], v[190:191], v[134:135] op_sel_hi:[0,1,1]
	v_pk_fma_f32 v[150:151], v[160:161], v[190:191], v[150:151] op_sel_hi:[0,1,1]
	s_waitcnt lgkmcnt(5)
	v_pk_fma_f32 v[136:137], v[252:253], v[232:233], v[136:137] op_sel_hi:[0,1,1]
	v_pk_fma_f32 v[152:153], v[160:161], v[232:233], v[152:153] op_sel_hi:[0,1,1]
	v_pk_fma_f32 v[138:139], v[252:253], v[234:235], v[138:139] op_sel_hi:[0,1,1]
	v_pk_fma_f32 v[154:155], v[160:161], v[234:235], v[154:155] op_sel_hi:[0,1,1]
	s_waitcnt lgkmcnt(4)
	v_pk_fma_f32 v[140:141], v[252:253], v[240:241], v[140:141] op_sel_hi:[0,1,1]
	v_pk_fma_f32 v[156:157], v[160:161], v[240:241], v[156:157] op_sel_hi:[0,1,1]
	v_pk_fma_f32 v[142:143], v[252:253], v[242:243], v[142:143] op_sel_hi:[0,1,1]
	v_pk_fma_f32 v[158:159], v[160:161], v[242:243], v[158:159] op_sel_hi:[0,1,1]
	ds_read_b128 v[184:187], v244 offset:53248
	ds_read_b128 v[188:191], v245 offset:53248
	ds_read_b128 v[232:235], v246 offset:53248
	ds_read_b128 v[240:243], v247 offset:53248
	v_mul_f32_e32 v252, v12, v212
	v_fmac_f32_e32 v254, v12, v12
	v_mul_f32_e32 v160, v44, v212
	v_fmac_f32_e32 v255, v44, v44
	s_waitcnt lgkmcnt(7)
	v_pk_fma_f32 v[128:129], v[252:253], v[168:169], v[128:129] op_sel_hi:[0,1,1]
	v_pk_fma_f32 v[144:145], v[160:161], v[168:169], v[144:145] op_sel_hi:[0,1,1]
	v_pk_fma_f32 v[130:131], v[252:253], v[170:171], v[130:131] op_sel_hi:[0,1,1]
	v_pk_fma_f32 v[146:147], v[160:161], v[170:171], v[146:147] op_sel_hi:[0,1,1]
	s_waitcnt lgkmcnt(6)
	v_pk_fma_f32 v[132:133], v[252:253], v[172:173], v[132:133] op_sel_hi:[0,1,1]
	v_pk_fma_f32 v[148:149], v[160:161], v[172:173], v[148:149] op_sel_hi:[0,1,1]
	v_pk_fma_f32 v[134:135], v[252:253], v[174:175], v[134:135] op_sel_hi:[0,1,1]
	v_pk_fma_f32 v[150:151], v[160:161], v[174:175], v[150:151] op_sel_hi:[0,1,1]
	s_waitcnt lgkmcnt(5)
	v_pk_fma_f32 v[136:137], v[252:253], v[176:177], v[136:137] op_sel_hi:[0,1,1]
	v_pk_fma_f32 v[152:153], v[160:161], v[176:177], v[152:153] op_sel_hi:[0,1,1]
	v_pk_fma_f32 v[138:139], v[252:253], v[178:179], v[138:139] op_sel_hi:[0,1,1]
	v_pk_fma_f32 v[154:155], v[160:161], v[178:179], v[154:155] op_sel_hi:[0,1,1]
	s_waitcnt lgkmcnt(4)
	v_pk_fma_f32 v[140:141], v[252:253], v[180:181], v[140:141] op_sel_hi:[0,1,1]
	v_pk_fma_f32 v[156:157], v[160:161], v[180:181], v[156:157] op_sel_hi:[0,1,1]
	v_pk_fma_f32 v[142:143], v[252:253], v[182:183], v[142:143] op_sel_hi:[0,1,1]
	v_pk_fma_f32 v[158:159], v[160:161], v[182:183], v[158:159] op_sel_hi:[0,1,1]
	ds_read_b128 v[168:171], v244 offset:57344
	ds_read_b128 v[172:175], v245 offset:57344
	ds_read_b128 v[176:179], v246 offset:57344
	ds_read_b128 v[180:183], v247 offset:57344
	v_mul_f32_e32 v252, v13, v213
	v_fmac_f32_e32 v254, v13, v13
	v_mul_f32_e32 v160, v45, v213
	v_fmac_f32_e32 v255, v45, v45
	s_waitcnt lgkmcnt(7)
	v_pk_fma_f32 v[128:129], v[252:253], v[184:185], v[128:129] op_sel_hi:[0,1,1]
	v_pk_fma_f32 v[144:145], v[160:161], v[184:185], v[144:145] op_sel_hi:[0,1,1]
	v_pk_fma_f32 v[130:131], v[252:253], v[186:187], v[130:131] op_sel_hi:[0,1,1]
	v_pk_fma_f32 v[146:147], v[160:161], v[186:187], v[146:147] op_sel_hi:[0,1,1]
	s_waitcnt lgkmcnt(6)
	v_pk_fma_f32 v[132:133], v[252:253], v[188:189], v[132:133] op_sel_hi:[0,1,1]
	v_pk_fma_f32 v[148:149], v[160:161], v[188:189], v[148:149] op_sel_hi:[0,1,1]
	v_pk_fma_f32 v[134:135], v[252:253], v[190:191], v[134:135] op_sel_hi:[0,1,1]
	v_pk_fma_f32 v[150:151], v[160:161], v[190:191], v[150:151] op_sel_hi:[0,1,1]
	s_waitcnt lgkmcnt(5)
	v_pk_fma_f32 v[136:137], v[252:253], v[232:233], v[136:137] op_sel_hi:[0,1,1]
	v_pk_fma_f32 v[152:153], v[160:161], v[232:233], v[152:153] op_sel_hi:[0,1,1]
	v_pk_fma_f32 v[138:139], v[252:253], v[234:235], v[138:139] op_sel_hi:[0,1,1]
	v_pk_fma_f32 v[154:155], v[160:161], v[234:235], v[154:155] op_sel_hi:[0,1,1]
	s_waitcnt lgkmcnt(4)
	v_pk_fma_f32 v[140:141], v[252:253], v[240:241], v[140:141] op_sel_hi:[0,1,1]
	v_pk_fma_f32 v[156:157], v[160:161], v[240:241], v[156:157] op_sel_hi:[0,1,1]
	v_pk_fma_f32 v[142:143], v[252:253], v[242:243], v[142:143] op_sel_hi:[0,1,1]
	v_pk_fma_f32 v[158:159], v[160:161], v[242:243], v[158:159] op_sel_hi:[0,1,1]
	ds_read_b128 v[184:187], v244 offset:61440
	ds_read_b128 v[188:191], v245 offset:61440
	ds_read_b128 v[232:235], v246 offset:61440
	ds_read_b128 v[240:243], v247 offset:61440
	v_mul_f32_e32 v252, v14, v214
	v_fmac_f32_e32 v254, v14, v14
	v_mul_f32_e32 v160, v46, v214
	v_fmac_f32_e32 v255, v46, v46
	s_waitcnt lgkmcnt(7)
	v_pk_fma_f32 v[128:129], v[252:253], v[168:169], v[128:129] op_sel_hi:[0,1,1]
	v_pk_fma_f32 v[144:145], v[160:161], v[168:169], v[144:145] op_sel_hi:[0,1,1]
	v_pk_fma_f32 v[130:131], v[252:253], v[170:171], v[130:131] op_sel_hi:[0,1,1]
	v_pk_fma_f32 v[146:147], v[160:161], v[170:171], v[146:147] op_sel_hi:[0,1,1]
	s_waitcnt lgkmcnt(6)
	v_pk_fma_f32 v[132:133], v[252:253], v[172:173], v[132:133] op_sel_hi:[0,1,1]
	v_pk_fma_f32 v[148:149], v[160:161], v[172:173], v[148:149] op_sel_hi:[0,1,1]
	v_pk_fma_f32 v[134:135], v[252:253], v[174:175], v[134:135] op_sel_hi:[0,1,1]
	v_pk_fma_f32 v[150:151], v[160:161], v[174:175], v[150:151] op_sel_hi:[0,1,1]
	s_waitcnt lgkmcnt(5)
	v_pk_fma_f32 v[136:137], v[252:253], v[176:177], v[136:137] op_sel_hi:[0,1,1]
	v_pk_fma_f32 v[152:153], v[160:161], v[176:177], v[152:153] op_sel_hi:[0,1,1]
	v_pk_fma_f32 v[138:139], v[252:253], v[178:179], v[138:139] op_sel_hi:[0,1,1]
	v_pk_fma_f32 v[154:155], v[160:161], v[178:179], v[154:155] op_sel_hi:[0,1,1]
	s_waitcnt lgkmcnt(4)
	v_pk_fma_f32 v[140:141], v[252:253], v[180:181], v[140:141] op_sel_hi:[0,1,1]
	v_pk_fma_f32 v[156:157], v[160:161], v[180:181], v[156:157] op_sel_hi:[0,1,1]
	v_pk_fma_f32 v[142:143], v[252:253], v[182:183], v[142:143] op_sel_hi:[0,1,1]
	v_pk_fma_f32 v[158:159], v[160:161], v[182:183], v[158:159] op_sel_hi:[0,1,1]
	ds_read_b128 v[168:171], v248 offset:0
	ds_read_b128 v[172:175], v249 offset:0
	ds_read_b128 v[176:179], v250 offset:0
	ds_read_b128 v[180:183], v251 offset:0
	v_mul_f32_e32 v252, v15, v215
	v_fmac_f32_e32 v254, v15, v15
	v_mul_f32_e32 v160, v47, v215
	v_fmac_f32_e32 v255, v47, v47
	s_waitcnt lgkmcnt(7)
	v_pk_fma_f32 v[128:129], v[252:253], v[184:185], v[128:129] op_sel_hi:[0,1,1]
	v_pk_fma_f32 v[144:145], v[160:161], v[184:185], v[144:145] op_sel_hi:[0,1,1]
	v_pk_fma_f32 v[130:131], v[252:253], v[186:187], v[130:131] op_sel_hi:[0,1,1]
	v_pk_fma_f32 v[146:147], v[160:161], v[186:187], v[146:147] op_sel_hi:[0,1,1]
	s_waitcnt lgkmcnt(6)
	v_pk_fma_f32 v[132:133], v[252:253], v[188:189], v[132:133] op_sel_hi:[0,1,1]
	v_pk_fma_f32 v[148:149], v[160:161], v[188:189], v[148:149] op_sel_hi:[0,1,1]
	v_pk_fma_f32 v[134:135], v[252:253], v[190:191], v[134:135] op_sel_hi:[0,1,1]
	v_pk_fma_f32 v[150:151], v[160:161], v[190:191], v[150:151] op_sel_hi:[0,1,1]
	s_waitcnt lgkmcnt(5)
	v_pk_fma_f32 v[136:137], v[252:253], v[232:233], v[136:137] op_sel_hi:[0,1,1]
	v_pk_fma_f32 v[152:153], v[160:161], v[232:233], v[152:153] op_sel_hi:[0,1,1]
	v_pk_fma_f32 v[138:139], v[252:253], v[234:235], v[138:139] op_sel_hi:[0,1,1]
	v_pk_fma_f32 v[154:155], v[160:161], v[234:235], v[154:155] op_sel_hi:[0,1,1]
	s_waitcnt lgkmcnt(4)
	v_pk_fma_f32 v[140:141], v[252:253], v[240:241], v[140:141] op_sel_hi:[0,1,1]
	v_pk_fma_f32 v[156:157], v[160:161], v[240:241], v[156:157] op_sel_hi:[0,1,1]
	v_pk_fma_f32 v[142:143], v[252:253], v[242:243], v[142:143] op_sel_hi:[0,1,1]
	v_pk_fma_f32 v[158:159], v[160:161], v[242:243], v[158:159] op_sel_hi:[0,1,1]
	ds_read_b128 v[184:187], v248 offset:4096
	ds_read_b128 v[188:191], v249 offset:4096
	ds_read_b128 v[232:235], v250 offset:4096
	ds_read_b128 v[240:243], v251 offset:4096
	v_mul_f32_e32 v252, v16, v216
	v_fmac_f32_e32 v254, v16, v16
	v_mul_f32_e32 v160, v48, v216
	v_fmac_f32_e32 v255, v48, v48
	s_waitcnt lgkmcnt(7)
	v_pk_fma_f32 v[128:129], v[252:253], v[168:169], v[128:129] op_sel_hi:[0,1,1]
	v_pk_fma_f32 v[144:145], v[160:161], v[168:169], v[144:145] op_sel_hi:[0,1,1]
	v_pk_fma_f32 v[130:131], v[252:253], v[170:171], v[130:131] op_sel_hi:[0,1,1]
	v_pk_fma_f32 v[146:147], v[160:161], v[170:171], v[146:147] op_sel_hi:[0,1,1]
	s_waitcnt lgkmcnt(6)
	v_pk_fma_f32 v[132:133], v[252:253], v[172:173], v[132:133] op_sel_hi:[0,1,1]
	v_pk_fma_f32 v[148:149], v[160:161], v[172:173], v[148:149] op_sel_hi:[0,1,1]
	v_pk_fma_f32 v[134:135], v[252:253], v[174:175], v[134:135] op_sel_hi:[0,1,1]
	v_pk_fma_f32 v[150:151], v[160:161], v[174:175], v[150:151] op_sel_hi:[0,1,1]
	s_waitcnt lgkmcnt(5)
	v_pk_fma_f32 v[136:137], v[252:253], v[176:177], v[136:137] op_sel_hi:[0,1,1]
	v_pk_fma_f32 v[152:153], v[160:161], v[176:177], v[152:153] op_sel_hi:[0,1,1]
	v_pk_fma_f32 v[138:139], v[252:253], v[178:179], v[138:139] op_sel_hi:[0,1,1]
	v_pk_fma_f32 v[154:155], v[160:161], v[178:179], v[154:155] op_sel_hi:[0,1,1]
	s_waitcnt lgkmcnt(4)
	v_pk_fma_f32 v[140:141], v[252:253], v[180:181], v[140:141] op_sel_hi:[0,1,1]
	v_pk_fma_f32 v[156:157], v[160:161], v[180:181], v[156:157] op_sel_hi:[0,1,1]
	v_pk_fma_f32 v[142:143], v[252:253], v[182:183], v[142:143] op_sel_hi:[0,1,1]
	v_pk_fma_f32 v[158:159], v[160:161], v[182:183], v[158:159] op_sel_hi:[0,1,1]
	ds_read_b128 v[168:171], v248 offset:8192
	ds_read_b128 v[172:175], v249 offset:8192
	ds_read_b128 v[176:179], v250 offset:8192
	ds_read_b128 v[180:183], v251 offset:8192
	v_mul_f32_e32 v252, v17, v217
	v_fmac_f32_e32 v254, v17, v17
	v_mul_f32_e32 v160, v49, v217
	v_fmac_f32_e32 v255, v49, v49
	s_waitcnt lgkmcnt(7)
	v_pk_fma_f32 v[128:129], v[252:253], v[184:185], v[128:129] op_sel_hi:[0,1,1]
	v_pk_fma_f32 v[144:145], v[160:161], v[184:185], v[144:145] op_sel_hi:[0,1,1]
	v_pk_fma_f32 v[130:131], v[252:253], v[186:187], v[130:131] op_sel_hi:[0,1,1]
	v_pk_fma_f32 v[146:147], v[160:161], v[186:187], v[146:147] op_sel_hi:[0,1,1]
	s_waitcnt lgkmcnt(6)
	v_pk_fma_f32 v[132:133], v[252:253], v[188:189], v[132:133] op_sel_hi:[0,1,1]
	v_pk_fma_f32 v[148:149], v[160:161], v[188:189], v[148:149] op_sel_hi:[0,1,1]
	v_pk_fma_f32 v[134:135], v[252:253], v[190:191], v[134:135] op_sel_hi:[0,1,1]
	v_pk_fma_f32 v[150:151], v[160:161], v[190:191], v[150:151] op_sel_hi:[0,1,1]
	s_waitcnt lgkmcnt(5)
	v_pk_fma_f32 v[136:137], v[252:253], v[232:233], v[136:137] op_sel_hi:[0,1,1]
	v_pk_fma_f32 v[152:153], v[160:161], v[232:233], v[152:153] op_sel_hi:[0,1,1]
	v_pk_fma_f32 v[138:139], v[252:253], v[234:235], v[138:139] op_sel_hi:[0,1,1]
	v_pk_fma_f32 v[154:155], v[160:161], v[234:235], v[154:155] op_sel_hi:[0,1,1]
	s_waitcnt lgkmcnt(4)
	v_pk_fma_f32 v[140:141], v[252:253], v[240:241], v[140:141] op_sel_hi:[0,1,1]
	v_pk_fma_f32 v[156:157], v[160:161], v[240:241], v[156:157] op_sel_hi:[0,1,1]
	v_pk_fma_f32 v[142:143], v[252:253], v[242:243], v[142:143] op_sel_hi:[0,1,1]
	v_pk_fma_f32 v[158:159], v[160:161], v[242:243], v[158:159] op_sel_hi:[0,1,1]
	ds_read_b128 v[184:187], v248 offset:12288
	ds_read_b128 v[188:191], v249 offset:12288
	ds_read_b128 v[232:235], v250 offset:12288
	ds_read_b128 v[240:243], v251 offset:12288
	v_mul_f32_e32 v252, v18, v218
	v_fmac_f32_e32 v254, v18, v18
	v_mul_f32_e32 v160, v50, v218
	v_fmac_f32_e32 v255, v50, v50
	s_waitcnt lgkmcnt(7)
	v_pk_fma_f32 v[128:129], v[252:253], v[168:169], v[128:129] op_sel_hi:[0,1,1]
	v_pk_fma_f32 v[144:145], v[160:161], v[168:169], v[144:145] op_sel_hi:[0,1,1]
	v_pk_fma_f32 v[130:131], v[252:253], v[170:171], v[130:131] op_sel_hi:[0,1,1]
	v_pk_fma_f32 v[146:147], v[160:161], v[170:171], v[146:147] op_sel_hi:[0,1,1]
	s_waitcnt lgkmcnt(6)
	v_pk_fma_f32 v[132:133], v[252:253], v[172:173], v[132:133] op_sel_hi:[0,1,1]
	v_pk_fma_f32 v[148:149], v[160:161], v[172:173], v[148:149] op_sel_hi:[0,1,1]
	v_pk_fma_f32 v[134:135], v[252:253], v[174:175], v[134:135] op_sel_hi:[0,1,1]
	v_pk_fma_f32 v[150:151], v[160:161], v[174:175], v[150:151] op_sel_hi:[0,1,1]
	s_waitcnt lgkmcnt(5)
	v_pk_fma_f32 v[136:137], v[252:253], v[176:177], v[136:137] op_sel_hi:[0,1,1]
	v_pk_fma_f32 v[152:153], v[160:161], v[176:177], v[152:153] op_sel_hi:[0,1,1]
	v_pk_fma_f32 v[138:139], v[252:253], v[178:179], v[138:139] op_sel_hi:[0,1,1]
	v_pk_fma_f32 v[154:155], v[160:161], v[178:179], v[154:155] op_sel_hi:[0,1,1]
	s_waitcnt lgkmcnt(4)
	v_pk_fma_f32 v[140:141], v[252:253], v[180:181], v[140:141] op_sel_hi:[0,1,1]
	v_pk_fma_f32 v[156:157], v[160:161], v[180:181], v[156:157] op_sel_hi:[0,1,1]
	v_pk_fma_f32 v[142:143], v[252:253], v[182:183], v[142:143] op_sel_hi:[0,1,1]
	v_pk_fma_f32 v[158:159], v[160:161], v[182:183], v[158:159] op_sel_hi:[0,1,1]
	ds_read_b128 v[168:171], v248 offset:16384
	ds_read_b128 v[172:175], v249 offset:16384
	ds_read_b128 v[176:179], v250 offset:16384
	ds_read_b128 v[180:183], v251 offset:16384
	v_mul_f32_e32 v252, v19, v219
	v_fmac_f32_e32 v254, v19, v19
	v_mul_f32_e32 v160, v51, v219
	v_fmac_f32_e32 v255, v51, v51
	s_waitcnt lgkmcnt(7)
	v_pk_fma_f32 v[128:129], v[252:253], v[184:185], v[128:129] op_sel_hi:[0,1,1]
	v_pk_fma_f32 v[144:145], v[160:161], v[184:185], v[144:145] op_sel_hi:[0,1,1]
	v_pk_fma_f32 v[130:131], v[252:253], v[186:187], v[130:131] op_sel_hi:[0,1,1]
	v_pk_fma_f32 v[146:147], v[160:161], v[186:187], v[146:147] op_sel_hi:[0,1,1]
	s_waitcnt lgkmcnt(6)
	v_pk_fma_f32 v[132:133], v[252:253], v[188:189], v[132:133] op_sel_hi:[0,1,1]
	v_pk_fma_f32 v[148:149], v[160:161], v[188:189], v[148:149] op_sel_hi:[0,1,1]
	v_pk_fma_f32 v[134:135], v[252:253], v[190:191], v[134:135] op_sel_hi:[0,1,1]
	v_pk_fma_f32 v[150:151], v[160:161], v[190:191], v[150:151] op_sel_hi:[0,1,1]
	s_waitcnt lgkmcnt(5)
	v_pk_fma_f32 v[136:137], v[252:253], v[232:233], v[136:137] op_sel_hi:[0,1,1]
	v_pk_fma_f32 v[152:153], v[160:161], v[232:233], v[152:153] op_sel_hi:[0,1,1]
	v_pk_fma_f32 v[138:139], v[252:253], v[234:235], v[138:139] op_sel_hi:[0,1,1]
	v_pk_fma_f32 v[154:155], v[160:161], v[234:235], v[154:155] op_sel_hi:[0,1,1]
	s_waitcnt lgkmcnt(4)
	v_pk_fma_f32 v[140:141], v[252:253], v[240:241], v[140:141] op_sel_hi:[0,1,1]
	v_pk_fma_f32 v[156:157], v[160:161], v[240:241], v[156:157] op_sel_hi:[0,1,1]
	v_pk_fma_f32 v[142:143], v[252:253], v[242:243], v[142:143] op_sel_hi:[0,1,1]
	v_pk_fma_f32 v[158:159], v[160:161], v[242:243], v[158:159] op_sel_hi:[0,1,1]
	ds_read_b128 v[184:187], v248 offset:20480
	ds_read_b128 v[188:191], v249 offset:20480
	ds_read_b128 v[232:235], v250 offset:20480
	ds_read_b128 v[240:243], v251 offset:20480
	v_mul_f32_e32 v252, v20, v220
	v_fmac_f32_e32 v254, v20, v20
	v_mul_f32_e32 v160, v52, v220
	v_fmac_f32_e32 v255, v52, v52
	s_waitcnt lgkmcnt(7)
	v_pk_fma_f32 v[128:129], v[252:253], v[168:169], v[128:129] op_sel_hi:[0,1,1]
	v_pk_fma_f32 v[144:145], v[160:161], v[168:169], v[144:145] op_sel_hi:[0,1,1]
	v_pk_fma_f32 v[130:131], v[252:253], v[170:171], v[130:131] op_sel_hi:[0,1,1]
	v_pk_fma_f32 v[146:147], v[160:161], v[170:171], v[146:147] op_sel_hi:[0,1,1]
	s_waitcnt lgkmcnt(6)
	v_pk_fma_f32 v[132:133], v[252:253], v[172:173], v[132:133] op_sel_hi:[0,1,1]
	v_pk_fma_f32 v[148:149], v[160:161], v[172:173], v[148:149] op_sel_hi:[0,1,1]
	v_pk_fma_f32 v[134:135], v[252:253], v[174:175], v[134:135] op_sel_hi:[0,1,1]
	v_pk_fma_f32 v[150:151], v[160:161], v[174:175], v[150:151] op_sel_hi:[0,1,1]
	s_waitcnt lgkmcnt(5)
	v_pk_fma_f32 v[136:137], v[252:253], v[176:177], v[136:137] op_sel_hi:[0,1,1]
	v_pk_fma_f32 v[152:153], v[160:161], v[176:177], v[152:153] op_sel_hi:[0,1,1]
	v_pk_fma_f32 v[138:139], v[252:253], v[178:179], v[138:139] op_sel_hi:[0,1,1]
	v_pk_fma_f32 v[154:155], v[160:161], v[178:179], v[154:155] op_sel_hi:[0,1,1]
	s_waitcnt lgkmcnt(4)
	v_pk_fma_f32 v[140:141], v[252:253], v[180:181], v[140:141] op_sel_hi:[0,1,1]
	v_pk_fma_f32 v[156:157], v[160:161], v[180:181], v[156:157] op_sel_hi:[0,1,1]
	v_pk_fma_f32 v[142:143], v[252:253], v[182:183], v[142:143] op_sel_hi:[0,1,1]
	v_pk_fma_f32 v[158:159], v[160:161], v[182:183], v[158:159] op_sel_hi:[0,1,1]
	ds_read_b128 v[168:171], v248 offset:24576
	ds_read_b128 v[172:175], v249 offset:24576
	ds_read_b128 v[176:179], v250 offset:24576
	ds_read_b128 v[180:183], v251 offset:24576
	v_mul_f32_e32 v252, v21, v221
	v_fmac_f32_e32 v254, v21, v21
	v_mul_f32_e32 v160, v53, v221
	v_fmac_f32_e32 v255, v53, v53
	s_waitcnt lgkmcnt(7)
	v_pk_fma_f32 v[128:129], v[252:253], v[184:185], v[128:129] op_sel_hi:[0,1,1]
	v_pk_fma_f32 v[144:145], v[160:161], v[184:185], v[144:145] op_sel_hi:[0,1,1]
	v_pk_fma_f32 v[130:131], v[252:253], v[186:187], v[130:131] op_sel_hi:[0,1,1]
	v_pk_fma_f32 v[146:147], v[160:161], v[186:187], v[146:147] op_sel_hi:[0,1,1]
	s_waitcnt lgkmcnt(6)
	v_pk_fma_f32 v[132:133], v[252:253], v[188:189], v[132:133] op_sel_hi:[0,1,1]
	v_pk_fma_f32 v[148:149], v[160:161], v[188:189], v[148:149] op_sel_hi:[0,1,1]
	v_pk_fma_f32 v[134:135], v[252:253], v[190:191], v[134:135] op_sel_hi:[0,1,1]
	v_pk_fma_f32 v[150:151], v[160:161], v[190:191], v[150:151] op_sel_hi:[0,1,1]
	s_waitcnt lgkmcnt(5)
	v_pk_fma_f32 v[136:137], v[252:253], v[232:233], v[136:137] op_sel_hi:[0,1,1]
	v_pk_fma_f32 v[152:153], v[160:161], v[232:233], v[152:153] op_sel_hi:[0,1,1]
	v_pk_fma_f32 v[138:139], v[252:253], v[234:235], v[138:139] op_sel_hi:[0,1,1]
	v_pk_fma_f32 v[154:155], v[160:161], v[234:235], v[154:155] op_sel_hi:[0,1,1]
	s_waitcnt lgkmcnt(4)
	v_pk_fma_f32 v[140:141], v[252:253], v[240:241], v[140:141] op_sel_hi:[0,1,1]
	v_pk_fma_f32 v[156:157], v[160:161], v[240:241], v[156:157] op_sel_hi:[0,1,1]
	v_pk_fma_f32 v[142:143], v[252:253], v[242:243], v[142:143] op_sel_hi:[0,1,1]
	v_pk_fma_f32 v[158:159], v[160:161], v[242:243], v[158:159] op_sel_hi:[0,1,1]
	ds_read_b128 v[184:187], v248 offset:28672
	ds_read_b128 v[188:191], v249 offset:28672
	ds_read_b128 v[232:235], v250 offset:28672
	ds_read_b128 v[240:243], v251 offset:28672
	v_mul_f32_e32 v252, v22, v222
	v_fmac_f32_e32 v254, v22, v22
	v_mul_f32_e32 v160, v54, v222
	v_fmac_f32_e32 v255, v54, v54
	s_waitcnt lgkmcnt(7)
	v_pk_fma_f32 v[128:129], v[252:253], v[168:169], v[128:129] op_sel_hi:[0,1,1]
	v_pk_fma_f32 v[144:145], v[160:161], v[168:169], v[144:145] op_sel_hi:[0,1,1]
	v_pk_fma_f32 v[130:131], v[252:253], v[170:171], v[130:131] op_sel_hi:[0,1,1]
	v_pk_fma_f32 v[146:147], v[160:161], v[170:171], v[146:147] op_sel_hi:[0,1,1]
	s_waitcnt lgkmcnt(6)
	v_pk_fma_f32 v[132:133], v[252:253], v[172:173], v[132:133] op_sel_hi:[0,1,1]
	v_pk_fma_f32 v[148:149], v[160:161], v[172:173], v[148:149] op_sel_hi:[0,1,1]
	v_pk_fma_f32 v[134:135], v[252:253], v[174:175], v[134:135] op_sel_hi:[0,1,1]
	v_pk_fma_f32 v[150:151], v[160:161], v[174:175], v[150:151] op_sel_hi:[0,1,1]
	s_waitcnt lgkmcnt(5)
	v_pk_fma_f32 v[136:137], v[252:253], v[176:177], v[136:137] op_sel_hi:[0,1,1]
	v_pk_fma_f32 v[152:153], v[160:161], v[176:177], v[152:153] op_sel_hi:[0,1,1]
	v_pk_fma_f32 v[138:139], v[252:253], v[178:179], v[138:139] op_sel_hi:[0,1,1]
	v_pk_fma_f32 v[154:155], v[160:161], v[178:179], v[154:155] op_sel_hi:[0,1,1]
	s_waitcnt lgkmcnt(4)
	v_pk_fma_f32 v[140:141], v[252:253], v[180:181], v[140:141] op_sel_hi:[0,1,1]
	v_pk_fma_f32 v[156:157], v[160:161], v[180:181], v[156:157] op_sel_hi:[0,1,1]
	v_pk_fma_f32 v[142:143], v[252:253], v[182:183], v[142:143] op_sel_hi:[0,1,1]
	v_pk_fma_f32 v[158:159], v[160:161], v[182:183], v[158:159] op_sel_hi:[0,1,1]
	ds_read_b128 v[168:171], v248 offset:32768
	ds_read_b128 v[172:175], v249 offset:32768
	ds_read_b128 v[176:179], v250 offset:32768
	ds_read_b128 v[180:183], v251 offset:32768
	v_mul_f32_e32 v252, v23, v223
	v_fmac_f32_e32 v254, v23, v23
	v_mul_f32_e32 v160, v55, v223
	v_fmac_f32_e32 v255, v55, v55
	s_waitcnt lgkmcnt(7)
	v_pk_fma_f32 v[128:129], v[252:253], v[184:185], v[128:129] op_sel_hi:[0,1,1]
	v_pk_fma_f32 v[144:145], v[160:161], v[184:185], v[144:145] op_sel_hi:[0,1,1]
	v_pk_fma_f32 v[130:131], v[252:253], v[186:187], v[130:131] op_sel_hi:[0,1,1]
	v_pk_fma_f32 v[146:147], v[160:161], v[186:187], v[146:147] op_sel_hi:[0,1,1]
	s_waitcnt lgkmcnt(6)
	v_pk_fma_f32 v[132:133], v[252:253], v[188:189], v[132:133] op_sel_hi:[0,1,1]
	v_pk_fma_f32 v[148:149], v[160:161], v[188:189], v[148:149] op_sel_hi:[0,1,1]
	v_pk_fma_f32 v[134:135], v[252:253], v[190:191], v[134:135] op_sel_hi:[0,1,1]
	v_pk_fma_f32 v[150:151], v[160:161], v[190:191], v[150:151] op_sel_hi:[0,1,1]
	s_waitcnt lgkmcnt(5)
	v_pk_fma_f32 v[136:137], v[252:253], v[232:233], v[136:137] op_sel_hi:[0,1,1]
	v_pk_fma_f32 v[152:153], v[160:161], v[232:233], v[152:153] op_sel_hi:[0,1,1]
	v_pk_fma_f32 v[138:139], v[252:253], v[234:235], v[138:139] op_sel_hi:[0,1,1]
	v_pk_fma_f32 v[154:155], v[160:161], v[234:235], v[154:155] op_sel_hi:[0,1,1]
	s_waitcnt lgkmcnt(4)
	v_pk_fma_f32 v[140:141], v[252:253], v[240:241], v[140:141] op_sel_hi:[0,1,1]
	v_pk_fma_f32 v[156:157], v[160:161], v[240:241], v[156:157] op_sel_hi:[0,1,1]
	v_pk_fma_f32 v[142:143], v[252:253], v[242:243], v[142:143] op_sel_hi:[0,1,1]
	v_pk_fma_f32 v[158:159], v[160:161], v[242:243], v[158:159] op_sel_hi:[0,1,1]
	ds_read_b128 v[184:187], v248 offset:36864
	ds_read_b128 v[188:191], v249 offset:36864
	ds_read_b128 v[232:235], v250 offset:36864
	ds_read_b128 v[240:243], v251 offset:36864
	v_mul_f32_e32 v252, v24, v224
	v_fmac_f32_e32 v254, v24, v24
	v_mul_f32_e32 v160, v56, v224
	v_fmac_f32_e32 v255, v56, v56
	s_waitcnt lgkmcnt(7)
	v_pk_fma_f32 v[128:129], v[252:253], v[168:169], v[128:129] op_sel_hi:[0,1,1]
	v_pk_fma_f32 v[144:145], v[160:161], v[168:169], v[144:145] op_sel_hi:[0,1,1]
	v_pk_fma_f32 v[130:131], v[252:253], v[170:171], v[130:131] op_sel_hi:[0,1,1]
	v_pk_fma_f32 v[146:147], v[160:161], v[170:171], v[146:147] op_sel_hi:[0,1,1]
	s_waitcnt lgkmcnt(6)
	v_pk_fma_f32 v[132:133], v[252:253], v[172:173], v[132:133] op_sel_hi:[0,1,1]
	v_pk_fma_f32 v[148:149], v[160:161], v[172:173], v[148:149] op_sel_hi:[0,1,1]
	v_pk_fma_f32 v[134:135], v[252:253], v[174:175], v[134:135] op_sel_hi:[0,1,1]
	v_pk_fma_f32 v[150:151], v[160:161], v[174:175], v[150:151] op_sel_hi:[0,1,1]
	s_waitcnt lgkmcnt(5)
	v_pk_fma_f32 v[136:137], v[252:253], v[176:177], v[136:137] op_sel_hi:[0,1,1]
	v_pk_fma_f32 v[152:153], v[160:161], v[176:177], v[152:153] op_sel_hi:[0,1,1]
	v_pk_fma_f32 v[138:139], v[252:253], v[178:179], v[138:139] op_sel_hi:[0,1,1]
	v_pk_fma_f32 v[154:155], v[160:161], v[178:179], v[154:155] op_sel_hi:[0,1,1]
	s_waitcnt lgkmcnt(4)
	v_pk_fma_f32 v[140:141], v[252:253], v[180:181], v[140:141] op_sel_hi:[0,1,1]
	v_pk_fma_f32 v[156:157], v[160:161], v[180:181], v[156:157] op_sel_hi:[0,1,1]
	v_pk_fma_f32 v[142:143], v[252:253], v[182:183], v[142:143] op_sel_hi:[0,1,1]
	v_pk_fma_f32 v[158:159], v[160:161], v[182:183], v[158:159] op_sel_hi:[0,1,1]
	ds_read_b128 v[168:171], v248 offset:40960
	ds_read_b128 v[172:175], v249 offset:40960
	ds_read_b128 v[176:179], v250 offset:40960
	ds_read_b128 v[180:183], v251 offset:40960
	v_mul_f32_e32 v252, v25, v225
	v_fmac_f32_e32 v254, v25, v25
	v_mul_f32_e32 v160, v57, v225
	v_fmac_f32_e32 v255, v57, v57
	s_waitcnt lgkmcnt(7)
	v_pk_fma_f32 v[128:129], v[252:253], v[184:185], v[128:129] op_sel_hi:[0,1,1]
	v_pk_fma_f32 v[144:145], v[160:161], v[184:185], v[144:145] op_sel_hi:[0,1,1]
	v_pk_fma_f32 v[130:131], v[252:253], v[186:187], v[130:131] op_sel_hi:[0,1,1]
	v_pk_fma_f32 v[146:147], v[160:161], v[186:187], v[146:147] op_sel_hi:[0,1,1]
	s_waitcnt lgkmcnt(6)
	v_pk_fma_f32 v[132:133], v[252:253], v[188:189], v[132:133] op_sel_hi:[0,1,1]
	v_pk_fma_f32 v[148:149], v[160:161], v[188:189], v[148:149] op_sel_hi:[0,1,1]
	v_pk_fma_f32 v[134:135], v[252:253], v[190:191], v[134:135] op_sel_hi:[0,1,1]
	v_pk_fma_f32 v[150:151], v[160:161], v[190:191], v[150:151] op_sel_hi:[0,1,1]
	s_waitcnt lgkmcnt(5)
	v_pk_fma_f32 v[136:137], v[252:253], v[232:233], v[136:137] op_sel_hi:[0,1,1]
	v_pk_fma_f32 v[152:153], v[160:161], v[232:233], v[152:153] op_sel_hi:[0,1,1]
	v_pk_fma_f32 v[138:139], v[252:253], v[234:235], v[138:139] op_sel_hi:[0,1,1]
	v_pk_fma_f32 v[154:155], v[160:161], v[234:235], v[154:155] op_sel_hi:[0,1,1]
	s_waitcnt lgkmcnt(4)
	v_pk_fma_f32 v[140:141], v[252:253], v[240:241], v[140:141] op_sel_hi:[0,1,1]
	v_pk_fma_f32 v[156:157], v[160:161], v[240:241], v[156:157] op_sel_hi:[0,1,1]
	v_pk_fma_f32 v[142:143], v[252:253], v[242:243], v[142:143] op_sel_hi:[0,1,1]
	v_pk_fma_f32 v[158:159], v[160:161], v[242:243], v[158:159] op_sel_hi:[0,1,1]
	ds_read_b128 v[184:187], v248 offset:45056
	ds_read_b128 v[188:191], v249 offset:45056
	ds_read_b128 v[232:235], v250 offset:45056
	ds_read_b128 v[240:243], v251 offset:45056
	v_mul_f32_e32 v252, v26, v226
	v_fmac_f32_e32 v254, v26, v26
	v_mul_f32_e32 v160, v58, v226
	v_fmac_f32_e32 v255, v58, v58
	s_waitcnt lgkmcnt(7)
	v_pk_fma_f32 v[128:129], v[252:253], v[168:169], v[128:129] op_sel_hi:[0,1,1]
	v_pk_fma_f32 v[144:145], v[160:161], v[168:169], v[144:145] op_sel_hi:[0,1,1]
	v_pk_fma_f32 v[130:131], v[252:253], v[170:171], v[130:131] op_sel_hi:[0,1,1]
	v_pk_fma_f32 v[146:147], v[160:161], v[170:171], v[146:147] op_sel_hi:[0,1,1]
	s_waitcnt lgkmcnt(6)
	v_pk_fma_f32 v[132:133], v[252:253], v[172:173], v[132:133] op_sel_hi:[0,1,1]
	v_pk_fma_f32 v[148:149], v[160:161], v[172:173], v[148:149] op_sel_hi:[0,1,1]
	v_pk_fma_f32 v[134:135], v[252:253], v[174:175], v[134:135] op_sel_hi:[0,1,1]
	v_pk_fma_f32 v[150:151], v[160:161], v[174:175], v[150:151] op_sel_hi:[0,1,1]
	s_waitcnt lgkmcnt(5)
	v_pk_fma_f32 v[136:137], v[252:253], v[176:177], v[136:137] op_sel_hi:[0,1,1]
	v_pk_fma_f32 v[152:153], v[160:161], v[176:177], v[152:153] op_sel_hi:[0,1,1]
	v_pk_fma_f32 v[138:139], v[252:253], v[178:179], v[138:139] op_sel_hi:[0,1,1]
	v_pk_fma_f32 v[154:155], v[160:161], v[178:179], v[154:155] op_sel_hi:[0,1,1]
	s_waitcnt lgkmcnt(4)
	v_pk_fma_f32 v[140:141], v[252:253], v[180:181], v[140:141] op_sel_hi:[0,1,1]
	v_pk_fma_f32 v[156:157], v[160:161], v[180:181], v[156:157] op_sel_hi:[0,1,1]
	v_pk_fma_f32 v[142:143], v[252:253], v[182:183], v[142:143] op_sel_hi:[0,1,1]
	v_pk_fma_f32 v[158:159], v[160:161], v[182:183], v[158:159] op_sel_hi:[0,1,1]
	ds_read_b128 v[168:171], v248 offset:49152
	ds_read_b128 v[172:175], v249 offset:49152
	ds_read_b128 v[176:179], v250 offset:49152
	ds_read_b128 v[180:183], v251 offset:49152
	v_mul_f32_e32 v252, v27, v227
	v_fmac_f32_e32 v254, v27, v27
	v_mul_f32_e32 v160, v59, v227
	v_fmac_f32_e32 v255, v59, v59
	s_waitcnt lgkmcnt(7)
	v_pk_fma_f32 v[128:129], v[252:253], v[184:185], v[128:129] op_sel_hi:[0,1,1]
	v_pk_fma_f32 v[144:145], v[160:161], v[184:185], v[144:145] op_sel_hi:[0,1,1]
	v_pk_fma_f32 v[130:131], v[252:253], v[186:187], v[130:131] op_sel_hi:[0,1,1]
	v_pk_fma_f32 v[146:147], v[160:161], v[186:187], v[146:147] op_sel_hi:[0,1,1]
	s_waitcnt lgkmcnt(6)
	v_pk_fma_f32 v[132:133], v[252:253], v[188:189], v[132:133] op_sel_hi:[0,1,1]
	v_pk_fma_f32 v[148:149], v[160:161], v[188:189], v[148:149] op_sel_hi:[0,1,1]
	v_pk_fma_f32 v[134:135], v[252:253], v[190:191], v[134:135] op_sel_hi:[0,1,1]
	v_pk_fma_f32 v[150:151], v[160:161], v[190:191], v[150:151] op_sel_hi:[0,1,1]
	s_waitcnt lgkmcnt(5)
	v_pk_fma_f32 v[136:137], v[252:253], v[232:233], v[136:137] op_sel_hi:[0,1,1]
	v_pk_fma_f32 v[152:153], v[160:161], v[232:233], v[152:153] op_sel_hi:[0,1,1]
	v_pk_fma_f32 v[138:139], v[252:253], v[234:235], v[138:139] op_sel_hi:[0,1,1]
	v_pk_fma_f32 v[154:155], v[160:161], v[234:235], v[154:155] op_sel_hi:[0,1,1]
	s_waitcnt lgkmcnt(4)
	v_pk_fma_f32 v[140:141], v[252:253], v[240:241], v[140:141] op_sel_hi:[0,1,1]
	v_pk_fma_f32 v[156:157], v[160:161], v[240:241], v[156:157] op_sel_hi:[0,1,1]
	v_pk_fma_f32 v[142:143], v[252:253], v[242:243], v[142:143] op_sel_hi:[0,1,1]
	v_pk_fma_f32 v[158:159], v[160:161], v[242:243], v[158:159] op_sel_hi:[0,1,1]
	ds_read_b128 v[184:187], v248 offset:53248
	ds_read_b128 v[188:191], v249 offset:53248
	ds_read_b128 v[232:235], v250 offset:53248
	ds_read_b128 v[240:243], v251 offset:53248
	v_mul_f32_e32 v252, v28, v228
	v_fmac_f32_e32 v254, v28, v28
	v_mul_f32_e32 v160, v60, v228
	v_fmac_f32_e32 v255, v60, v60
	s_waitcnt lgkmcnt(7)
	v_pk_fma_f32 v[128:129], v[252:253], v[168:169], v[128:129] op_sel_hi:[0,1,1]
	v_pk_fma_f32 v[144:145], v[160:161], v[168:169], v[144:145] op_sel_hi:[0,1,1]
	v_pk_fma_f32 v[130:131], v[252:253], v[170:171], v[130:131] op_sel_hi:[0,1,1]
	v_pk_fma_f32 v[146:147], v[160:161], v[170:171], v[146:147] op_sel_hi:[0,1,1]
	s_waitcnt lgkmcnt(6)
	v_pk_fma_f32 v[132:133], v[252:253], v[172:173], v[132:133] op_sel_hi:[0,1,1]
	v_pk_fma_f32 v[148:149], v[160:161], v[172:173], v[148:149] op_sel_hi:[0,1,1]
	v_pk_fma_f32 v[134:135], v[252:253], v[174:175], v[134:135] op_sel_hi:[0,1,1]
	v_pk_fma_f32 v[150:151], v[160:161], v[174:175], v[150:151] op_sel_hi:[0,1,1]
	s_waitcnt lgkmcnt(5)
	v_pk_fma_f32 v[136:137], v[252:253], v[176:177], v[136:137] op_sel_hi:[0,1,1]
	v_pk_fma_f32 v[152:153], v[160:161], v[176:177], v[152:153] op_sel_hi:[0,1,1]
	v_pk_fma_f32 v[138:139], v[252:253], v[178:179], v[138:139] op_sel_hi:[0,1,1]
	v_pk_fma_f32 v[154:155], v[160:161], v[178:179], v[154:155] op_sel_hi:[0,1,1]
	s_waitcnt lgkmcnt(4)
	v_pk_fma_f32 v[140:141], v[252:253], v[180:181], v[140:141] op_sel_hi:[0,1,1]
	v_pk_fma_f32 v[156:157], v[160:161], v[180:181], v[156:157] op_sel_hi:[0,1,1]
	v_pk_fma_f32 v[142:143], v[252:253], v[182:183], v[142:143] op_sel_hi:[0,1,1]
	v_pk_fma_f32 v[158:159], v[160:161], v[182:183], v[158:159] op_sel_hi:[0,1,1]
	ds_read_b128 v[168:171], v248 offset:57344
	ds_read_b128 v[172:175], v249 offset:57344
	ds_read_b128 v[176:179], v250 offset:57344
	ds_read_b128 v[180:183], v251 offset:57344
	v_mul_f32_e32 v252, v29, v229
	v_fmac_f32_e32 v254, v29, v29
	v_mul_f32_e32 v160, v61, v229
	v_fmac_f32_e32 v255, v61, v61
	s_waitcnt lgkmcnt(7)
	v_pk_fma_f32 v[128:129], v[252:253], v[184:185], v[128:129] op_sel_hi:[0,1,1]
	v_pk_fma_f32 v[144:145], v[160:161], v[184:185], v[144:145] op_sel_hi:[0,1,1]
	v_pk_fma_f32 v[130:131], v[252:253], v[186:187], v[130:131] op_sel_hi:[0,1,1]
	v_pk_fma_f32 v[146:147], v[160:161], v[186:187], v[146:147] op_sel_hi:[0,1,1]
	s_waitcnt lgkmcnt(6)
	v_pk_fma_f32 v[132:133], v[252:253], v[188:189], v[132:133] op_sel_hi:[0,1,1]
	v_pk_fma_f32 v[148:149], v[160:161], v[188:189], v[148:149] op_sel_hi:[0,1,1]
	v_pk_fma_f32 v[134:135], v[252:253], v[190:191], v[134:135] op_sel_hi:[0,1,1]
	v_pk_fma_f32 v[150:151], v[160:161], v[190:191], v[150:151] op_sel_hi:[0,1,1]
	s_waitcnt lgkmcnt(5)
	v_pk_fma_f32 v[136:137], v[252:253], v[232:233], v[136:137] op_sel_hi:[0,1,1]
	v_pk_fma_f32 v[152:153], v[160:161], v[232:233], v[152:153] op_sel_hi:[0,1,1]
	v_pk_fma_f32 v[138:139], v[252:253], v[234:235], v[138:139] op_sel_hi:[0,1,1]
	v_pk_fma_f32 v[154:155], v[160:161], v[234:235], v[154:155] op_sel_hi:[0,1,1]
	s_waitcnt lgkmcnt(4)
	v_pk_fma_f32 v[140:141], v[252:253], v[240:241], v[140:141] op_sel_hi:[0,1,1]
	v_pk_fma_f32 v[156:157], v[160:161], v[240:241], v[156:157] op_sel_hi:[0,1,1]
	v_pk_fma_f32 v[142:143], v[252:253], v[242:243], v[142:143] op_sel_hi:[0,1,1]
	v_pk_fma_f32 v[158:159], v[160:161], v[242:243], v[158:159] op_sel_hi:[0,1,1]
	ds_read_b128 v[184:187], v248 offset:61440
	ds_read_b128 v[188:191], v249 offset:61440
	ds_read_b128 v[232:235], v250 offset:61440
	ds_read_b128 v[240:243], v251 offset:61440
	v_mul_f32_e32 v252, v30, v230
	v_fmac_f32_e32 v254, v30, v30
	v_mul_f32_e32 v160, v62, v230
	v_fmac_f32_e32 v255, v62, v62
	s_waitcnt lgkmcnt(7)
	v_pk_fma_f32 v[128:129], v[252:253], v[168:169], v[128:129] op_sel_hi:[0,1,1]
	v_pk_fma_f32 v[144:145], v[160:161], v[168:169], v[144:145] op_sel_hi:[0,1,1]
	v_pk_fma_f32 v[130:131], v[252:253], v[170:171], v[130:131] op_sel_hi:[0,1,1]
	v_pk_fma_f32 v[146:147], v[160:161], v[170:171], v[146:147] op_sel_hi:[0,1,1]
	s_waitcnt lgkmcnt(6)
	v_pk_fma_f32 v[132:133], v[252:253], v[172:173], v[132:133] op_sel_hi:[0,1,1]
	v_pk_fma_f32 v[148:149], v[160:161], v[172:173], v[148:149] op_sel_hi:[0,1,1]
	v_pk_fma_f32 v[134:135], v[252:253], v[174:175], v[134:135] op_sel_hi:[0,1,1]
	v_pk_fma_f32 v[150:151], v[160:161], v[174:175], v[150:151] op_sel_hi:[0,1,1]
	s_waitcnt lgkmcnt(5)
	v_pk_fma_f32 v[136:137], v[252:253], v[176:177], v[136:137] op_sel_hi:[0,1,1]
	v_pk_fma_f32 v[152:153], v[160:161], v[176:177], v[152:153] op_sel_hi:[0,1,1]
	v_pk_fma_f32 v[138:139], v[252:253], v[178:179], v[138:139] op_sel_hi:[0,1,1]
	v_pk_fma_f32 v[154:155], v[160:161], v[178:179], v[154:155] op_sel_hi:[0,1,1]
	s_waitcnt lgkmcnt(4)
	v_pk_fma_f32 v[140:141], v[252:253], v[180:181], v[140:141] op_sel_hi:[0,1,1]
	v_pk_fma_f32 v[156:157], v[160:161], v[180:181], v[156:157] op_sel_hi:[0,1,1]
	v_pk_fma_f32 v[142:143], v[252:253], v[182:183], v[142:143] op_sel_hi:[0,1,1]
	v_pk_fma_f32 v[158:159], v[160:161], v[182:183], v[158:159] op_sel_hi:[0,1,1]
	v_mul_f32_e32 v252, v31, v231
	v_fmac_f32_e32 v254, v31, v31
	v_mul_f32_e32 v160, v63, v231
	v_fmac_f32_e32 v255, v63, v63
	s_waitcnt lgkmcnt(3)
	v_pk_fma_f32 v[128:129], v[252:253], v[184:185], v[128:129] op_sel_hi:[0,1,1]
	v_pk_fma_f32 v[144:145], v[160:161], v[184:185], v[144:145] op_sel_hi:[0,1,1]
	v_pk_fma_f32 v[130:131], v[252:253], v[186:187], v[130:131] op_sel_hi:[0,1,1]
	v_pk_fma_f32 v[146:147], v[160:161], v[186:187], v[146:147] op_sel_hi:[0,1,1]
	s_waitcnt lgkmcnt(2)
	v_pk_fma_f32 v[132:133], v[252:253], v[188:189], v[132:133] op_sel_hi:[0,1,1]
	v_pk_fma_f32 v[148:149], v[160:161], v[188:189], v[148:149] op_sel_hi:[0,1,1]
	v_pk_fma_f32 v[134:135], v[252:253], v[190:191], v[134:135] op_sel_hi:[0,1,1]
	v_pk_fma_f32 v[150:151], v[160:161], v[190:191], v[150:151] op_sel_hi:[0,1,1]
	s_waitcnt lgkmcnt(1)
	v_pk_fma_f32 v[136:137], v[252:253], v[232:233], v[136:137] op_sel_hi:[0,1,1]
	v_pk_fma_f32 v[152:153], v[160:161], v[232:233], v[152:153] op_sel_hi:[0,1,1]
	v_pk_fma_f32 v[138:139], v[252:253], v[234:235], v[138:139] op_sel_hi:[0,1,1]
	v_pk_fma_f32 v[154:155], v[160:161], v[234:235], v[154:155] op_sel_hi:[0,1,1]
	s_waitcnt lgkmcnt(0)
	v_pk_fma_f32 v[140:141], v[252:253], v[240:241], v[140:141] op_sel_hi:[0,1,1]
	v_pk_fma_f32 v[156:157], v[160:161], v[240:241], v[156:157] op_sel_hi:[0,1,1]
	v_pk_fma_f32 v[142:143], v[252:253], v[242:243], v[142:143] op_sel_hi:[0,1,1]
	v_pk_fma_f32 v[158:159], v[160:161], v[242:243], v[158:159] op_sel_hi:[0,1,1]
	v_xor_b32_e32 v162, 32, v197
	v_lshlrev_b32_e32 v162, 2, v162
	ds_bpermute_b32 v160, v162, v254
	ds_bpermute_b32 v161, v162, v255
	s_waitcnt lgkmcnt(0)
	v_add_f32_e32 v254, v254, v160
	v_add_f32_e32 v255, v255, v161
	v_xor_b32_e32 v162, 16, v197
	v_lshlrev_b32_e32 v162, 2, v162
	ds_bpermute_b32 v160, v162, v254
	ds_bpermute_b32 v161, v162, v255
	s_waitcnt lgkmcnt(0)
	v_add_f32_e32 v254, v254, v160
	v_add_f32_e32 v255, v255, v161
	v_xor_b32_e32 v162, 8, v197
	v_lshlrev_b32_e32 v162, 2, v162
	ds_bpermute_b32 v160, v162, v254
	ds_bpermute_b32 v161, v162, v255
	s_waitcnt lgkmcnt(0)
	v_add_f32_e32 v254, v254, v160
	v_add_f32_e32 v255, v255, v161
	v_xor_b32_e32 v162, 4, v197
	v_lshlrev_b32_e32 v162, 2, v162
	ds_bpermute_b32 v160, v162, v254
	ds_bpermute_b32 v161, v162, v255
	s_waitcnt lgkmcnt(0)
	v_add_f32_e32 v254, v254, v160
	v_add_f32_e32 v255, v255, v161
	v_xor_b32_e32 v162, 2, v197
	v_lshlrev_b32_e32 v162, 2, v162
	ds_bpermute_b32 v160, v162, v254
	ds_bpermute_b32 v161, v162, v255
	s_waitcnt lgkmcnt(0)
	v_add_f32_e32 v254, v254, v160
	v_add_f32_e32 v255, v255, v161
	v_xor_b32_e32 v162, 1, v197
	v_lshlrev_b32_e32 v162, 2, v162
	ds_bpermute_b32 v160, v162, v254
	ds_bpermute_b32 v161, v162, v255
	s_waitcnt lgkmcnt(0)
	v_add_f32_e32 v254, v254, v160
	v_add_f32_e32 v255, v255, v161
	v_mov_b32_e32 v160, 0x358637bd
	v_fma_f32 v254, v254, s20, v160
	v_fma_f32 v255, v255, s20, v160
	v_rsq_f32_e32 v254, v254
	v_rsq_f32_e32 v255, v255
	s_nop 0
	s_lshl_b32 s18, s16, 12
	s_add_u32 s22, s6, s18
	s_addc_u32 s23, s7, 0
	v_mul_f32_e32 v163, v0, v254
	v_mul_f32_e32 v165, v1, v254
	v_mul_f32_e32 v167, v2, v254
	v_mul_f32_e32 v199, v3, v254
	v_mul_f32_e32 v163, v163, v200
	v_mul_f32_e32 v165, v165, v201
	v_mul_f32_e32 v167, v167, v202
	v_mul_f32_e32 v199, v199, v203
	v_cvt_pk_bf16_f32 v192, v163, v165
	v_cvt_pk_bf16_f32 v193, v167, v199
	global_store_dwordx2 v164, v[192:193], s[22:23] offset:0
	v_mul_f32_e32 v163, v4, v254
	v_mul_f32_e32 v165, v5, v254
	v_mul_f32_e32 v167, v6, v254
	v_mul_f32_e32 v199, v7, v254
	v_mul_f32_e32 v163, v163, v204
	v_mul_f32_e32 v165, v165, v205
	v_mul_f32_e32 v167, v167, v206
	v_mul_f32_e32 v199, v199, v207
	v_cvt_pk_bf16_f32 v238, v163, v165
	v_cvt_pk_bf16_f32 v239, v167, v199
	global_store_dwordx2 v164, v[238:239], s[22:23] offset:512
	v_mul_f32_e32 v163, v8, v254
	v_mul_f32_e32 v165, v9, v254
	v_mul_f32_e32 v167, v10, v254
	v_mul_f32_e32 v199, v11, v254
	v_mul_f32_e32 v163, v163, v208
	v_mul_f32_e32 v165, v165, v209
	v_mul_f32_e32 v167, v167, v210
	v_mul_f32_e32 v199, v199, v211
	v_cvt_pk_bf16_f32 v192, v163, v165
	v_cvt_pk_bf16_f32 v193, v167, v199
	global_store_dwordx2 v164, v[192:193], s[22:23] offset:1024
	v_mul_f32_e32 v163, v12, v254
	v_mul_f32_e32 v165, v13, v254
	v_mul_f32_e32 v167, v14, v254
	v_mul_f32_e32 v199, v15, v254
	v_mul_f32_e32 v163, v163, v212
	v_mul_f32_e32 v165, v165, v213
	v_mul_f32_e32 v167, v167, v214
	v_mul_f32_e32 v199, v199, v215
	v_cvt_pk_bf16_f32 v238, v163, v165
	v_cvt_pk_bf16_f32 v239, v167, v199
	global_store_dwordx2 v164, v[238:239], s[22:23] offset:1536
	v_mul_f32_e32 v163, v16, v254
	v_mul_f32_e32 v165, v17, v254
	v_mul_f32_e32 v167, v18, v254
	v_mul_f32_e32 v199, v19, v254
	v_mul_f32_e32 v163, v163, v216
	v_mul_f32_e32 v165, v165, v217
	v_mul_f32_e32 v167, v167, v218
	v_mul_f32_e32 v199, v199, v219
	v_cvt_pk_bf16_f32 v192, v163, v165
	v_cvt_pk_bf16_f32 v193, v167, v199
	global_store_dwordx2 v164, v[192:193], s[22:23] offset:2048
	v_mul_f32_e32 v163, v20, v254
	v_mul_f32_e32 v165, v21, v254
	v_mul_f32_e32 v167, v22, v254
	v_mul_f32_e32 v199, v23, v254
	v_mul_f32_e32 v163, v163, v220
	v_mul_f32_e32 v165, v165, v221
	v_mul_f32_e32 v167, v167, v222
	v_mul_f32_e32 v199, v199, v223
	v_cvt_pk_bf16_f32 v238, v163, v165
	v_cvt_pk_bf16_f32 v239, v167, v199
	global_store_dwordx2 v164, v[238:239], s[22:23] offset:2560
	v_mul_f32_e32 v163, v24, v254
	v_mul_f32_e32 v165, v25, v254
	v_mul_f32_e32 v167, v26, v254
	v_mul_f32_e32 v199, v27, v254
	v_mul_f32_e32 v163, v163, v224
	v_mul_f32_e32 v165, v165, v225
	v_mul_f32_e32 v167, v167, v226
	v_mul_f32_e32 v199, v199, v227
	v_cvt_pk_bf16_f32 v192, v163, v165
	v_cvt_pk_bf16_f32 v193, v167, v199
	global_store_dwordx2 v164, v[192:193], s[22:23] offset:3072
	v_mul_f32_e32 v163, v28, v254
	v_mul_f32_e32 v165, v29, v254
	v_mul_f32_e32 v167, v30, v254
	v_mul_f32_e32 v199, v31, v254
	v_mul_f32_e32 v163, v163, v228
	v_mul_f32_e32 v165, v165, v229
	v_mul_f32_e32 v167, v167, v230
	v_mul_f32_e32 v199, v199, v231
	v_cvt_pk_bf16_f32 v238, v163, v165
	v_cvt_pk_bf16_f32 v239, v167, v199
	global_store_dwordx2 v164, v[238:239], s[22:23] offset:3584
	s_add_u32 s22, s22, 0x1000
	s_addc_u32 s23, s23, 0
	v_mul_f32_e32 v163, v32, v255
	v_mul_f32_e32 v165, v33, v255
	v_mul_f32_e32 v167, v34, v255
	v_mul_f32_e32 v199, v35, v255
	v_mul_f32_e32 v163, v163, v200
	v_mul_f32_e32 v165, v165, v201
	v_mul_f32_e32 v167, v167, v202
	v_mul_f32_e32 v199, v199, v203
	v_cvt_pk_bf16_f32 v192, v163, v165
	v_cvt_pk_bf16_f32 v193, v167, v199
	global_store_dwordx2 v164, v[192:193], s[22:23] offset:0
	v_mul_f32_e32 v163, v36, v255
	v_mul_f32_e32 v165, v37, v255
	v_mul_f32_e32 v167, v38, v255
	v_mul_f32_e32 v199, v39, v255
	v_mul_f32_e32 v163, v163, v204
	v_mul_f32_e32 v165, v165, v205
	v_mul_f32_e32 v167, v167, v206
	v_mul_f32_e32 v199, v199, v207
	v_cvt_pk_bf16_f32 v238, v163, v165
	v_cvt_pk_bf16_f32 v239, v167, v199
	global_store_dwordx2 v164, v[238:239], s[22:23] offset:512
	v_mul_f32_e32 v163, v40, v255
	v_mul_f32_e32 v165, v41, v255
	v_mul_f32_e32 v167, v42, v255
	v_mul_f32_e32 v199, v43, v255
	v_mul_f32_e32 v163, v163, v208
	v_mul_f32_e32 v165, v165, v209
	v_mul_f32_e32 v167, v167, v210
	v_mul_f32_e32 v199, v199, v211
	v_cvt_pk_bf16_f32 v192, v163, v165
	v_cvt_pk_bf16_f32 v193, v167, v199
	global_store_dwordx2 v164, v[192:193], s[22:23] offset:1024
	v_mul_f32_e32 v163, v44, v255
	v_mul_f32_e32 v165, v45, v255
	v_mul_f32_e32 v167, v46, v255
	v_mul_f32_e32 v199, v47, v255
	v_mul_f32_e32 v163, v163, v212
	v_mul_f32_e32 v165, v165, v213
	v_mul_f32_e32 v167, v167, v214
	v_mul_f32_e32 v199, v199, v215
	v_cvt_pk_bf16_f32 v238, v163, v165
	v_cvt_pk_bf16_f32 v239, v167, v199
	global_store_dwordx2 v164, v[238:239], s[22:23] offset:1536
	v_mul_f32_e32 v163, v48, v255
	v_mul_f32_e32 v165, v49, v255
	v_mul_f32_e32 v167, v50, v255
	v_mul_f32_e32 v199, v51, v255
	v_mul_f32_e32 v163, v163, v216
	v_mul_f32_e32 v165, v165, v217
	v_mul_f32_e32 v167, v167, v218
	v_mul_f32_e32 v199, v199, v219
	v_cvt_pk_bf16_f32 v192, v163, v165
	v_cvt_pk_bf16_f32 v193, v167, v199
	global_store_dwordx2 v164, v[192:193], s[22:23] offset:2048
	v_mul_f32_e32 v163, v52, v255
	v_mul_f32_e32 v165, v53, v255
	v_mul_f32_e32 v167, v54, v255
	v_mul_f32_e32 v199, v55, v255
	v_mul_f32_e32 v163, v163, v220
	v_mul_f32_e32 v165, v165, v221
	v_mul_f32_e32 v167, v167, v222
	v_mul_f32_e32 v199, v199, v223
	v_cvt_pk_bf16_f32 v238, v163, v165
	v_cvt_pk_bf16_f32 v239, v167, v199
	global_store_dwordx2 v164, v[238:239], s[22:23] offset:2560
	v_mul_f32_e32 v163, v56, v255
	v_mul_f32_e32 v165, v57, v255
	v_mul_f32_e32 v167, v58, v255
	v_mul_f32_e32 v199, v59, v255
	v_mul_f32_e32 v163, v163, v224
	v_mul_f32_e32 v165, v165, v225
	v_mul_f32_e32 v167, v167, v226
	v_mul_f32_e32 v199, v199, v227
	v_cvt_pk_bf16_f32 v192, v163, v165
	v_cvt_pk_bf16_f32 v193, v167, v199
	global_store_dwordx2 v164, v[192:193], s[22:23] offset:3072
	v_mul_f32_e32 v163, v60, v255
	v_mul_f32_e32 v165, v61, v255
	v_mul_f32_e32 v167, v62, v255
	v_mul_f32_e32 v199, v63, v255
	v_mul_f32_e32 v163, v163, v228
	v_mul_f32_e32 v165, v165, v229
	v_mul_f32_e32 v167, v167, v230
	v_mul_f32_e32 v199, v199, v231
	v_cvt_pk_bf16_f32 v238, v163, v165
	v_cvt_pk_bf16_f32 v239, v167, v199
	global_store_dwordx2 v164, v[238:239], s[22:23] offset:3584
	v_xor_b32_e32 v162, 32, v197
	v_lshlrev_b32_e32 v162, 2, v162
	v_cndmask_b32_e64 v163, v144, v128, s[24:25]
	v_cndmask_b32_e64 v128, v128, v144, s[24:25]
	ds_bpermute_b32 v144, v162, v163
	v_cndmask_b32_e64 v165, v145, v129, s[24:25]
	v_cndmask_b32_e64 v129, v129, v145, s[24:25]
	ds_bpermute_b32 v145, v162, v165
	v_cndmask_b32_e64 v167, v146, v130, s[24:25]
	v_cndmask_b32_e64 v130, v130, v146, s[24:25]
	ds_bpermute_b32 v146, v162, v167
	v_cndmask_b32_e64 v199, v147, v131, s[24:25]
	v_cndmask_b32_e64 v131, v131, v147, s[24:25]
	ds_bpermute_b32 v147, v162, v199
	v_cndmask_b32_e64 v163, v148, v132, s[24:25]
	v_cndmask_b32_e64 v132, v132, v148, s[24:25]
	ds_bpermute_b32 v148, v162, v163
	v_cndmask_b32_e64 v165, v149, v133, s[24:25]
	v_cndmask_b32_e64 v133, v133, v149, s[24:25]
	ds_bpermute_b32 v149, v162, v165
	v_cndmask_b32_e64 v167, v150, v134, s[24:25]
	v_cndmask_b32_e64 v134, v134, v150, s[24:25]
	ds_bpermute_b32 v150, v162, v167
	v_cndmask_b32_e64 v199, v151, v135, s[24:25]
	v_cndmask_b32_e64 v135, v135, v151, s[24:25]
	ds_bpermute_b32 v151, v162, v199
	s_waitcnt lgkmcnt(0)
	v_add_f32_e32 v128, v128, v144
	v_add_f32_e32 v129, v129, v145
	v_add_f32_e32 v130, v130, v146
	v_add_f32_e32 v131, v131, v147
	v_add_f32_e32 v132, v132, v148
	v_add_f32_e32 v133, v133, v149
	v_add_f32_e32 v134, v134, v150
	v_add_f32_e32 v135, v135, v151
	v_cndmask_b32_e64 v163, v152, v136, s[24:25]
	v_cndmask_b32_e64 v136, v136, v152, s[24:25]
	ds_bpermute_b32 v152, v162, v163
	v_cndmask_b32_e64 v165, v153, v137, s[24:25]
	v_cndmask_b32_e64 v137, v137, v153, s[24:25]
	ds_bpermute_b32 v153, v162, v165
	v_cndmask_b32_e64 v167, v154, v138, s[24:25]
	v_cndmask_b32_e64 v138, v138, v154, s[24:25]
	ds_bpermute_b32 v154, v162, v167
	v_cndmask_b32_e64 v199, v155, v139, s[24:25]
	v_cndmask_b32_e64 v139, v139, v155, s[24:25]
	ds_bpermute_b32 v155, v162, v199
	v_cndmask_b32_e64 v163, v156, v140, s[24:25]
	v_cndmask_b32_e64 v140, v140, v156, s[24:25]
	ds_bpermute_b32 v156, v162, v163
	v_cndmask_b32_e64 v165, v157, v141, s[24:25]
	v_cndmask_b32_e64 v141, v141, v157, s[24:25]
	ds_bpermute_b32 v157, v162, v165
	v_cndmask_b32_e64 v167, v158, v142, s[24:25]
	v_cndmask_b32_e64 v142, v142, v158, s[24:25]
	ds_bpermute_b32 v158, v162, v167
	v_cndmask_b32_e64 v199, v159, v143, s[24:25]
	v_cndmask_b32_e64 v143, v143, v159, s[24:25]
	ds_bpermute_b32 v159, v162, v199
	s_waitcnt lgkmcnt(0)
	v_add_f32_e32 v136, v136, v152
	v_add_f32_e32 v137, v137, v153
	v_add_f32_e32 v138, v138, v154
	v_add_f32_e32 v139, v139, v155
	v_add_f32_e32 v140, v140, v156
	v_add_f32_e32 v141, v141, v157
	v_add_f32_e32 v142, v142, v158
	v_add_f32_e32 v143, v143, v159
	v_xor_b32_e32 v162, 16, v197
	v_lshlrev_b32_e32 v162, 2, v162
	v_cndmask_b32_e64 v163, v136, v128, s[26:27]
	v_cndmask_b32_e64 v128, v128, v136, s[26:27]
	ds_bpermute_b32 v136, v162, v163
	v_cndmask_b32_e64 v165, v137, v129, s[26:27]
	v_cndmask_b32_e64 v129, v129, v137, s[26:27]
	ds_bpermute_b32 v137, v162, v165
	v_cndmask_b32_e64 v167, v138, v130, s[26:27]
	v_cndmask_b32_e64 v130, v130, v138, s[26:27]
	ds_bpermute_b32 v138, v162, v167
	v_cndmask_b32_e64 v199, v139, v131, s[26:27]
	v_cndmask_b32_e64 v131, v131, v139, s[26:27]
	ds_bpermute_b32 v139, v162, v199
	v_cndmask_b32_e64 v163, v140, v132, s[26:27]
	v_cndmask_b32_e64 v132, v132, v140, s[26:27]
	ds_bpermute_b32 v140, v162, v163
	v_cndmask_b32_e64 v165, v141, v133, s[26:27]
	v_cndmask_b32_e64 v133, v133, v141, s[26:27]
	ds_bpermute_b32 v141, v162, v165
	v_cndmask_b32_e64 v167, v142, v134, s[26:27]
	v_cndmask_b32_e64 v134, v134, v142, s[26:27]
	ds_bpermute_b32 v142, v162, v167
	v_cndmask_b32_e64 v199, v143, v135, s[26:27]
	v_cndmask_b32_e64 v135, v135, v143, s[26:27]
	ds_bpermute_b32 v143, v162, v199
	s_waitcnt lgkmcnt(0)
	v_add_f32_e32 v128, v128, v136
	v_add_f32_e32 v129, v129, v137
	v_add_f32_e32 v130, v130, v138
	v_add_f32_e32 v131, v131, v139
	v_add_f32_e32 v132, v132, v140
	v_add_f32_e32 v133, v133, v141
	v_add_f32_e32 v134, v134, v142
	v_add_f32_e32 v135, v135, v143
	v_xor_b32_e32 v162, 8, v197
	v_lshlrev_b32_e32 v162, 2, v162
	v_cndmask_b32_e64 v163, v132, v128, s[28:29]
	v_cndmask_b32_e64 v128, v128, v132, s[28:29]
	ds_bpermute_b32 v132, v162, v163
	v_cndmask_b32_e64 v165, v133, v129, s[28:29]
	v_cndmask_b32_e64 v129, v129, v133, s[28:29]
	ds_bpermute_b32 v133, v162, v165
	v_cndmask_b32_e64 v167, v134, v130, s[28:29]
	v_cndmask_b32_e64 v130, v130, v134, s[28:29]
	ds_bpermute_b32 v134, v162, v167
	v_cndmask_b32_e64 v199, v135, v131, s[28:29]
	v_cndmask_b32_e64 v131, v131, v135, s[28:29]
	ds_bpermute_b32 v135, v162, v199
	s_waitcnt lgkmcnt(0)
	v_add_f32_e32 v128, v128, v132
	v_add_f32_e32 v129, v129, v133
	v_add_f32_e32 v130, v130, v134
	v_add_f32_e32 v131, v131, v135
	v_xor_b32_e32 v162, 4, v197
	v_lshlrev_b32_e32 v162, 2, v162
	v_cndmask_b32_e64 v163, v130, v128, s[30:31]
	v_cndmask_b32_e64 v128, v128, v130, s[30:31]
	ds_bpermute_b32 v130, v162, v163
	v_cndmask_b32_e64 v165, v131, v129, s[30:31]
	v_cndmask_b32_e64 v129, v129, v131, s[30:31]
	ds_bpermute_b32 v131, v162, v165
	s_waitcnt lgkmcnt(0)
	v_add_f32_e32 v128, v128, v130
	v_add_f32_e32 v129, v129, v131
	v_xor_b32_e32 v162, 2, v197
	v_lshlrev_b32_e32 v162, 2, v162
	v_cndmask_b32_e64 v163, v129, v128, s[34:35]
	v_cndmask_b32_e64 v128, v128, v129, s[34:35]
	ds_bpermute_b32 v129, v162, v163
	s_waitcnt lgkmcnt(0)
	v_add_f32_e32 v128, v128, v129
	v_xor_b32_e32 v162, 1, v197
	v_lshlrev_b32_e32 v162, 2, v162
	ds_bpermute_b32 v160, v162, v128
	s_waitcnt lgkmcnt(0)
	v_add_f32_e32 v128, v128, v160
	v_cndmask_b32_e64 v160, v254, v255, s[24:25]
	v_mul_f32_e32 v128, v128, v160
	v_mul_f32_e32 v163, 0xbfb8aa3b, v128
	v_exp_f32_e32 v163, v163
	v_add_f32_e32 v167, v128, v195
	v_add_f32_e32 v163, 1.0, v163
	v_and_b32_e32 v199, 0x7fffffff, v167
	v_mul_f32_e32 v199, 0xbfb8aa3b, v199
	v_exp_f32_e32 v199, v199
	v_rcp_f32_e32 v163, v163
	v_add_f32_e32 v160, 1.0, v199
	v_log_f32_e32 v160, v160
	v_mul_f32_e32 v161, v199, v199
	v_mul_f32_e32 v160, 0x3f317218, v160
	v_mul_f32_e32 v162, v161, v199
	v_fma_f32 v161, v161, -0.5, v199
	v_mov_b32_e32 v165, 0x3eaaaaab
	v_fmac_f32_e32 v161, v162, v165
	v_cmp_gt_f32_e32 vcc, 0x3c800000, v199
	v_max_f32_e32 v167, 0, v167
	s_nop 0
	v_cndmask_b32_e32 v160, v160, v161, vcc
	v_add_f32_e32 v167, v167, v160
	v_mul_f32_e64 v165, -v237, v167
	v_bfe_u32 v162, v197, 1, 4
	v_cmp_gt_u32_e32 vcc, 8, v162
	v_and_b32_e32 v162, 7, v162
	s_lshr_b32 s18, s16, 11
	s_lshl_b32 s18, s18, 3
	v_add_u32_e32 v162, s18, v162
	v_lshlrev_b32_e32 v162, 13, v162
	s_and_b32 s18, s16, 2047
	v_lshrrev_b32_e32 v161, 5, v197
	v_add_u32_e32 v161, s18, v161
	v_lshl_add_u32 v162, v161, 2, v162
	v_cndmask_b32_e32 v160, v165, v163, vcc
	v_and_b32_e32 v161, 1, v197
	v_cmp_eq_u32_e64 s[22:23], 0, v161
	s_nop 1
	s_and_b64 s[0:1], s[22:23], vcc
	s_andn2_b64 s[2:3], s[22:23], vcc
	s_mov_b64 s[22:23], exec
	s_mov_b64 exec, s[0:1]
	global_store_dword v162, v160, s[12:13]
	s_mov_b64 exec, s[2:3]
	global_store_dword v162, v160, s[14:15]
	s_mov_b64 exec, s[22:23]
	s_add_u32 s16, s16, 2
	s_add_u32 s17, s17, 1
	s_cmp_lt_u32 s17, 4
	s_cbranch_scc1 .Lp0_loop
	v_lshrrev_b32_e32 v136, 4, v198
	v_lshrrev_b32_e32 v145, 3, v198
	v_lshlrev_b32_e32 v144, 3, v198
	v_readlane_b32 s72, v236, 22
	v_readlane_b32 s73, v236, 23
	v_readlane_b32 s74, v236, 24
	v_readlane_b32 s75, v236, 25
	v_readlane_b32 s76, v236, 26
	v_readlane_b32 s77, v236, 27
	v_readlane_b32 s78, v236, 28
	v_readlane_b32 s79, v236, 29
	v_readlane_b32 s80, v236, 30
	v_readlane_b32 s81, v236, 31
	v_readlane_b32 s82, v236, 32
	v_readlane_b32 s83, v236, 33
	v_readlane_b32 s84, v236, 34
	v_readlane_b32 s85, v236, 35
	v_readlane_b32 s86, v236, 36
	v_readlane_b32 s87, v236, 37
	s_nop 3
